# speedup vs baseline: 1.0621x; 1.0142x over previous
; DI void nsa_attn_phase(const Params& p, char* smem) {
;   constexpr long LD = 3584;
;   float* imp = (float*)(smem + SM_IMP);
;   unsigned* selm = (unsigned*)(smem + SM_SEL);
;   unsigned* um = (unsigned*)(smem + SM_UM);
;   for (;;) {
;     const int task = fetch_task(p.ctr + 0, smem);
.LBB0_799:
	s_mov_b32 s98, 0
	s_load_dword s99, s[56:57], 0x170
	v_writelane_b32 v255, s24, 12
	s_mov_b32 s0, 0xc1300000
	s_load_dwordx4 s[4:7], s[56:57], 0x100
	v_writelane_b32 v255, s25, 13
	v_writelane_b32 v255, s0, 14
	s_mov_b32 s64, 0x41000000
	s_mov_b32 s68, 0x41900000
	v_writelane_b32 v255, s1, 15
	s_mov_b32 s0, 0xc1d80000
	v_writelane_b32 v255, s0, 18
	s_mov_b32 s70, 0x41c00000
	s_mov_b32 s72, 0x41d00000
	v_writelane_b32 v255, s1, 19
	s_mov_b32 s0, 0xc22c0000
	v_writelane_b32 v255, s0, 22
	s_mov_b32 s74, 0x42680000
	s_mov_b32 s76, 0x42600000
	v_writelane_b32 v255, s1, 23
	s_waitcnt lgkmcnt(0)
	v_writelane_b32 v255, s4, 24
	s_mov_b32 s78, 0x42480000
	s_mov_b32 s80, 0x42400000
	v_writelane_b32 v255, s5, 25
	v_writelane_b32 v255, s6, 26
	v_writelane_b32 v255, s7, 27
	s_load_dwordx4 s[4:7], s[56:57], 0x128
	s_mov_b32 s82, 0x42280000
	s_mov_b32 s84, 0x42200000
	s_mov_b32 s86, 0x42080000
	s_mov_b32 s88, 0x42000000
	s_waitcnt lgkmcnt(0)
	v_writelane_b32 v255, s4, 28
	v_mov_b32_e32 v1, 0
	v_mov_b32_e32 v206, 0x12020
	v_writelane_b32 v255, s5, 29
	v_writelane_b32 v255, s6, 30
	v_writelane_b32 v255, s7, 31
	s_load_dwordx4 s[4:7], s[56:57], 0x150
	s_movk_i32 s33, 0x1c00
	v_mov_b32_e32 v207, 0x260
	s_mov_b32 s65, 0x41100000
	s_mov_b32 s69, 0x41980000
	s_waitcnt lgkmcnt(0)
	v_writelane_b32 v255, s4, 32
	s_mov_b32 s71, 0x41c80000
	s_mov_b32 s73, 0x41d80000
	v_writelane_b32 v255, s5, 33
	v_writelane_b32 v255, s6, 34
	s_mov_b32 s75, 0x426c0000
	s_mov_b32 s77, 0x42640000
	s_mov_b32 s79, 0x424c0000
	s_mov_b32 s81, 0x42440000
	s_mov_b32 s83, 0x422c0000
	s_mov_b32 s85, 0x42240000
	s_mov_b32 s87, 0x420c0000
	s_mov_b32 s89, 0x42040000
	v_mov_b32_e32 v208, 0xc000
	v_mov_b32_e32 v209, 0x42800000
	v_not_b32_e32 v210, 63
	v_mov_b32_e32 v211, 0x10000
	v_mov_b32_e32 v212, 0x10200
	v_mov_b32_e32 v213, 0x12000
	v_mov_b32_e32 v214, 0xff800000
	v_mov_b32_e32 v215, 0x4000
	v_mov_b32_e32 v216, 0x80
	v_mov_b32_e32 v217, 0x100
	v_mov_b32_e32 v218, 0x200
	v_mov_b32_e32 v219, 0x400
	v_mov_b32_e32 v220, 0x800
	v_mov_b32_e32 v221, 0x1000
	v_mov_b32_e32 v223, 0x2000
	v_mov_b32_e32 v224, 0x8000
	v_mov_b32_e32 v225, 0x100000
	s_mov_b32 s2, 0x4e000000
	s_mov_b32 s3, 0xc3160000
	s_movk_i32 s60, 0x7f
	s_brev_b32 s61, 34
	v_writelane_b32 v255, s7, 35
	s_branch .LBB0_803

; DI int ltid() { int x = threadIdx.x; asm volatile("" : "+v"(x)); return x; }
; DI int fetch_task(unsigned* ctr, char* smem) {
;   unsigned* slot = (unsigned*)(smem + SM_TASK);
;   __syncthreads();
;   if (ltid() == 0) *slot = atomicAdd(ctr, 1u);
;   __syncthreads();
;   return (int)*slot;
; }
; DI void nsa_attn_phase(const Params& p, char* smem) {
;     ...
;     const int task = fetch_task(p.ctr + 0, smem);
;     if (task >= 2048) break;
;     const int tid = ltid(), lane = tid & 63, wid = tid >> 6, r = lane & 31, h = lane >> 5;
;     const int qt = 255 - (task >> 3), bh = task & 7, b = bh >> 2, hk = bh & 3;
;     const int hq = hk * 4 + wid;
;     const int t0 = qt * 32, tq = t0 + r;
;     const long tok = (long)b * SEQ + tq;
;     const float slope2 = exp2f(-0.5f * (float)(hq + 1)) * LOG2E;
;     bf16x8 qf[4];
;     load_q(qf, p.qkvz + tok * LD + hq * 64, h);
;     const float qb_s = q_bound(qf, p.kmax2[b * 64 + 24 + hk]), qb_w = q_bound(qf, p.kmax2[b * 64 + 32 + hk]);
;     const float* gp = p.gates + tok * 48;
;     const float g_c = gp[hq], g_s = gp[16 + hq], g_w = gp[32 + hq];
;     __syncthreads();
;     {
;       const int tz = ltid();
;       for (int i = tz; i < 32 * 128; i += 256) imp[i] = 0.f;
;       if (tz < 128) selm[tz] = 0u;
.LBB0_803:
	v_mov_b32_e32 v0, v222
	s_barrier
	s_nop 0
	v_cmp_eq_u32_e32 vcc, 0, v0
	s_and_saveexec_b64 s[0:1], vcc
	s_cbranch_execz .LBB0_807
	s_mov_b64 s[6:7], exec
	v_mbcnt_lo_u32_b32 v0, s6, 0
	v_mbcnt_hi_u32_b32 v0, s7, v0
	v_cmp_eq_u32_e32 vcc, 0, v0
	s_and_saveexec_b64 s[4:5], vcc
	s_cbranch_execz .LBB0_806
	s_bcnt1_i32_b64 s6, s[6:7]
	v_readlane_b32 s8, v255, 24
	v_mov_b32_e32 v2, s6
	v_readlane_b32 s10, v255, 26
	v_readlane_b32 s11, v255, 27
	v_readlane_b32 s9, v255, 25
	s_nop 3
	s_cmp_eq_u32 s98, 0
	s_cbranch_scc1 .Lft_skip_nsa
	global_atomic_add v2, v1, v2, s[10:11] sc0
.Lft_skip_nsa:
.LBB0_806:
	s_or_b64 exec, exec, s[4:5]
	s_waitcnt vmcnt(0)
	v_readfirstlane_b32 s4, v2
	s_nop 1
	v_add_u32_e32 v0, s4, v0
	s_waitcnt lgkmcnt(0)
	v_add_u32_e32 v0, s99, v0
	s_cmp_eq_u32 s98, 0
	s_cbranch_scc0 .Lft_st_nsa
	v_readlane_b32 s100, v255, 2
	s_nop 1
	v_mov_b32_e32 v0, s100
.Lft_st_nsa:
	ds_write_b32 v206, v0
.LBB0_807:
	s_or_b64 exec, exec, s[0:1]
	s_waitcnt lgkmcnt(0)
	s_barrier
	ds_read_b32 v0, v206
	s_mov_b32 s98, 1
	s_movk_i32 s0, 0x7ff
	s_waitcnt lgkmcnt(0)
	v_cmp_lt_i32_e32 vcc, s0, v0
	v_readfirstlane_b32 s20, v0
	s_mov_b64 s[0:1], -1
	s_cbranch_vccnz .LBB0_802
	v_mov_b32_e32 v105, v222
	s_and_b32 s0, s20, 3
	s_lshl_b32 s5, s0, 2
	v_ashrrev_i32_e32 v107, 6, v105
	v_add_u32_e32 v2, s5, v107
	s_bfe_u32 s4, s20, 0x10002
	v_add_u32_e32 v0, 1, v2
	v_writelane_b32 v255, s0, 36
	s_lshl_b32 s63, s20, 2
	s_lshl_b32 s0, s4, 13
	v_cvt_f32_i32_e32 v7, v0
	s_andn2_b32 s63, s63, 31
	v_writelane_b32 v255, s0, 37
	v_and_b32_e32 v104, 31, v105
	s_sub_i32 s62, 0x1fe0, s63
	v_readlane_b32 s8, v255, 28
	v_or_b32_e32 v227, s62, v104
	v_readlane_b32 s10, v255, 30
	v_readlane_b32 s11, v255, 31
	v_add_u32_e32 v176, s0, v227
	v_mul_f32_e32 v0, -0.5, v7
	s_mov_b32 s0, 0xc2fc0000
	v_mov_b64_e32 v[4:5], s[10:11]
	v_lshlrev_b32_e32 v180, 6, v2
	v_bfe_u32 v226, v105, 5, 1
	v_cmp_gt_f32_e32 vcc, s0, v0
	v_mad_u64_u32 v[178:179], s[0:1], v176, s33, v[4:5]
	v_ashrrev_i32_e32 v181, 31, v180
	v_lshl_add_u64 v[4:5], v[180:181], 1, v[178:179]
	v_lshlrev_b32_e32 v0, 4, v226
	v_lshl_add_u64 v[4:5], v[4:5], 0, v[0:1]
	global_load_dwordx4 v[160:163], v[4:5], off
	global_load_dwordx4 v[164:167], v[4:5], off offset:32
	global_load_dwordx4 v[168:171], v[4:5], off offset:64
	global_load_dwordx4 v[172:175], v[4:5], off offset:96
	s_lshl_b32 s0, s4, 8
	s_or_b32 s0, s0, s5
	v_readlane_b32 s12, v255, 24
	v_mov_b32_e32 v3, s0
	v_readlane_b32 s13, v255, 25
	s_mov_b32 s0, 0xf800000
	v_readlane_b32 s9, v255, 29
	v_readlane_b32 s14, v255, 26
	v_readlane_b32 s15, v255, 27
	s_mov_b32 s21, 0xf800000
	global_load_dword v0, v3, s[12:13] offset:96
	s_waitcnt vmcnt(4)
	v_and_b32_e32 v5, 0xffff0000, v160
	global_load_dword v3, v3, s[12:13] offset:128
	v_lshlrev_b32_e32 v4, 16, v160
	v_mul_f32_e32 v6, v5, v5
	v_fmac_f32_e32 v6, v4, v4
	v_lshlrev_b32_e32 v4, 16, v161
	v_fmac_f32_e32 v6, v4, v4
	v_and_b32_e32 v4, 0xffff0000, v161
	v_fmac_f32_e32 v6, v4, v4
	v_lshlrev_b32_e32 v4, 16, v162
	v_fmac_f32_e32 v6, v4, v4
	v_and_b32_e32 v4, 0xffff0000, v162
	v_fmac_f32_e32 v6, v4, v4
	v_lshlrev_b32_e32 v4, 16, v163
	v_fmac_f32_e32 v6, v4, v4
	v_and_b32_e32 v4, 0xffff0000, v163
	v_fmac_f32_e32 v6, v4, v4
	s_waitcnt vmcnt(4)
	v_lshlrev_b32_e32 v4, 16, v164
	v_fmac_f32_e32 v6, v4, v4
	v_and_b32_e32 v4, 0xffff0000, v164
	v_fmac_f32_e32 v6, v4, v4
	v_lshlrev_b32_e32 v4, 16, v165
	v_fmac_f32_e32 v6, v4, v4
	v_and_b32_e32 v4, 0xffff0000, v165
	v_fmac_f32_e32 v6, v4, v4
	v_lshlrev_b32_e32 v4, 16, v166
	v_fmac_f32_e32 v6, v4, v4
	v_and_b32_e32 v4, 0xffff0000, v166
	v_fmac_f32_e32 v6, v4, v4
	v_lshlrev_b32_e32 v4, 16, v167
	v_fmac_f32_e32 v6, v4, v4
	v_and_b32_e32 v4, 0xffff0000, v167
	v_fmac_f32_e32 v6, v4, v4
	s_waitcnt vmcnt(3)
	v_lshlrev_b32_e32 v4, 16, v168
	v_fmac_f32_e32 v6, v4, v4
	v_and_b32_e32 v4, 0xffff0000, v168
	v_fmac_f32_e32 v6, v4, v4
	v_lshlrev_b32_e32 v4, 16, v169
	v_fmac_f32_e32 v6, v4, v4
	v_and_b32_e32 v4, 0xffff0000, v169
	v_fmac_f32_e32 v6, v4, v4
	v_lshlrev_b32_e32 v4, 16, v170
	v_fmac_f32_e32 v6, v4, v4
	v_and_b32_e32 v4, 0xffff0000, v170
	v_fmac_f32_e32 v6, v4, v4
	v_lshlrev_b32_e32 v4, 16, v171
	v_fmac_f32_e32 v6, v4, v4
	v_and_b32_e32 v4, 0xffff0000, v171
	v_fmac_f32_e32 v6, v4, v4
	s_waitcnt vmcnt(2)
	v_lshlrev_b32_e32 v4, 16, v172
	v_fmac_f32_e32 v6, v4, v4
	v_and_b32_e32 v4, 0xffff0000, v172
	v_fmac_f32_e32 v6, v4, v4
	v_lshlrev_b32_e32 v4, 16, v173
	v_fmac_f32_e32 v6, v4, v4
	v_and_b32_e32 v4, 0xffff0000, v173
	v_fmac_f32_e32 v6, v4, v4
	v_lshlrev_b32_e32 v4, 16, v174
	v_fmac_f32_e32 v6, v4, v4
	v_and_b32_e32 v4, 0xffff0000, v174
	v_fmac_f32_e32 v6, v4, v4
	v_lshlrev_b32_e32 v4, 16, v175
	v_fmac_f32_e32 v6, v4, v4
	v_and_b32_e32 v4, 0xffff0000, v175
	v_fmac_f32_e32 v6, v4, v4
	v_mov_b32_e32 v4, v6
	v_mov_b32_e32 v5, v6
	s_nop 1
	v_permlane32_swap_b32_e32 v4, v5
	v_add_f32_e32 v4, v4, v5
	s_waitcnt vmcnt(1)
	v_mul_f32_e32 v0, v0, v4
	v_cmp_gt_f32_e64 s[4:5], s0, v0
	v_mul_f32_e32 v5, 0x4f800000, v0
	s_waitcnt vmcnt(0)
	v_mul_f32_e32 v3, v3, v4
	v_cndmask_b32_e64 v0, v0, v5, s[4:5]
	v_cmp_gt_f32_e64 s[6:7], s0, v3
	v_mul_f32_e32 v4, 0x4f800000, v3
	v_sqrt_f32_e32 v8, v0
	v_cndmask_b32_e64 v10, v3, v4, s[6:7]
	v_readlane_b32 s0, v255, 0
	v_sqrt_f32_e32 v12, v10
	v_readlane_b32 s1, v255, 1
	s_load_dwordx2 s[0:1], s[0:1], 0x140
	v_add_u32_e32 v9, -1, v8
	v_fma_f32 v5, -v9, v8, v0
	v_add_u32_e32 v11, 1, v8
	v_add_u32_e32 v13, -1, v12
	v_cmp_ge_f32_e64 s[8:9], 0, v5
	v_fma_f32 v5, -v11, v8, v0
	v_fma_f32 v3, -v13, v12, v10
	v_add_u32_e32 v14, 1, v12
	v_cmp_lt_f32_e64 s[10:11], 0, v5
	v_cmp_ge_f32_e64 s[12:13], 0, v3
	v_fma_f32 v3, -v14, v12, v10
	s_waitcnt lgkmcnt(0)
	v_mov_b64_e32 v[4:5], s[0:1]
	s_movk_i32 s0, 0xc0
	v_cmp_lt_f32_e64 s[14:15], 0, v3
	v_mad_u64_u32 v[4:5], s[0:1], v176, s0, v[4:5]
	v_ashrrev_i32_e32 v3, 31, v2
	v_lshl_add_u64 v[2:3], v[2:3], 2, v[4:5]
	global_load_dword v229, v[2:3], off
	global_load_dword v228, v[2:3], off offset:64
	global_load_dword v181, v[2:3], off offset:128
	v_mov_b32_e32 v2, v222
	s_movk_i32 s0, 0x1000
	s_barrier
	s_nop 0
	v_cmp_gt_i32_e64 s[16:17], s0, v2
	s_and_saveexec_b64 s[0:1], s[16:17]
	s_cbranch_execz .LBB0_811
	v_lshl_add_u32 v3, v2, 2, v208
	v_add_u32_e32 v4, 0xffffff00, v2
	s_mov_b64 s[18:19], 0

; DI int ltid() { int x = threadIdx.x; asm volatile("" : "+v"(x)); return x; }
; DI void diff_attn_phase(const Params& p, char* smem) {
;   const int lane0 = ltid() & 63;
;   constexpr long LD = 4096;
;   float la = p.b_lambda[lane0] * p.b_lambda[64 + lane0], lb = p.b_lambda[128 + lane0] * p.b_lambda[192 + lane0];
; #pragma unroll
;   for (int o = 32; o > 0; o >>= 1) { la += __shfl_xor(la, o); lb += __shfl_xor(lb, o); }
;   const float lambda_init = 0.8f - 0.6f * expf(-0.3f);
;   const float lam = expf(la) - expf(lb) + lambda_init;
;   for (;;) {
;     const int slot = fetch_task(p.ctr + 1, smem);
.LBB0_1471:
	s_mov_b32 s98, 0
	s_load_dword s99, s[56:57], 0x170
	s_waitcnt vmcnt(0)
	v_mov_b32_e32 v0, v222
	s_load_dwordx4 s[12:15], s[56:57], 0x68
	s_load_dwordx4 s[0:3], s[56:57], 0x100
	v_and_b32_e32 v0, 63, v0
	v_lshlrev_b32_e32 v0, 2, v0
	s_waitcnt lgkmcnt(0)
	global_load_dword v2, v0, s[12:13]
	global_load_dword v3, v0, s[12:13] offset:256
	global_load_dword v4, v0, s[12:13] offset:512
	global_load_dword v5, v0, s[12:13] offset:768
	v_mbcnt_lo_u32_b32 v0, -1, 0
	v_mbcnt_hi_u32_b32 v0, -1, v0
	v_and_b32_e32 v7, 64, v0
	v_xor_b32_e32 v8, 32, v0
	v_add_u32_e32 v7, 64, v7
	v_cmp_lt_i32_e32 vcc, v8, v7
	v_xor_b32_e32 v9, 16, v0
	v_xor_b32_e32 v10, 8, v0
	v_cndmask_b32_e32 v8, v0, v8, vcc
	v_lshlrev_b32_e32 v8, 2, v8
	v_cmp_lt_i32_e32 vcc, v9, v7
	v_xor_b32_e32 v11, 4, v0
	v_xor_b32_e32 v12, 2, v0
	v_cndmask_b32_e32 v9, v0, v9, vcc
	v_lshlrev_b32_e32 v9, 2, v9
	v_cmp_lt_i32_e32 vcc, v10, v7
	v_xor_b32_e32 v13, 1, v0
	v_writelane_b32 v255, s24, 18
	v_mov_b32_e32 v6, 0x7f800000
	s_load_dwordx2 s[62:63], s[56:57], 0x130
	s_load_dwordx4 s[20:23], s[56:57], 0x120
	v_writelane_b32 v255, s25, 19
	v_writelane_b32 v255, s0, 14
	s_mov_b32 s26, 2.0
	s_mov_b32 s28, 0x41000000
	v_writelane_b32 v255, s1, 15
	v_writelane_b32 v255, s2, 16
	v_writelane_b32 v255, s3, 17
	s_mov_b32 s2, 0x3fb8aa3b
	s_mov_b32 s1, 0xc2ce8ed0
	s_mov_b32 s0, 0x42b17218
	s_mov_b32 s30, 0x41200000
	s_mov_b32 s34, 0x41800000
	s_mov_b32 s36, 0x41900000
	s_mov_b32 s38, 0x41c00000
	s_mov_b32 s40, 0x41d00000
	s_mov_b32 s42, 0x42680000
	s_mov_b32 s44, 0x42600000
	s_mov_b32 s46, 0x42480000
	s_mov_b32 s48, 0x42400000
	s_mov_b32 s50, 0x42280000
	s_mov_b32 s52, 0x42200000
	s_mov_b32 s54, 0x42080000
	s_mov_b32 s58, 0x42000000
	s_mov_b32 s60, -1.0
	s_mov_b32 s64, 0xc0400000
	s_mov_b32 s66, 0xc1100000
	s_mov_b32 s68, 0xc1300000
	s_mov_b32 s70, 0xc1880000
	s_mov_b32 s72, 0xc1980000
	s_mov_b32 s74, 0xc1c80000
	s_mov_b32 s76, 0xc1d80000
	s_mov_b32 s78, 0xc2040000
	s_mov_b32 s80, 0xc20c0000
	s_mov_b32 s82, 0xc2240000
	s_mov_b32 s84, 0xc22c0000
	s_mov_b32 s86, 0xc2440000
	s_mov_b32 s88, 0xc24c0000
	s_mov_b32 s90, 0xc2640000
	s_mov_b32 s3, 0
	v_mov_b32_e32 v1, 0
	v_mov_b32_e32 v148, 0x12020
	v_mov_b32_e32 v149, 0x260
	s_mov_b64 s[12:13], 0x800
	s_mov_b32 s27, 0x40400000
	s_mov_b32 s29, 0x41100000
	s_mov_b32 s31, 0x41300000
	s_mov_b32 s35, 0x41880000
	s_mov_b32 s37, 0x41980000
	s_mov_b32 s39, 0x41c80000
	s_mov_b32 s41, 0x41d80000
	s_mov_b32 s43, 0x426c0000
	s_mov_b32 s45, 0x42640000
	s_mov_b32 s47, 0x424c0000
	s_mov_b32 s49, 0x42440000
	s_mov_b32 s51, 0x422c0000
	s_mov_b32 s53, 0x42240000
	s_mov_b32 s55, 0x420c0000
	s_waitcnt vmcnt(2)
	v_mul_f32_e32 v14, v2, v3
	ds_bpermute_b32 v14, v8, v14
	s_waitcnt vmcnt(0)
	v_mul_f32_e32 v15, v4, v5
	ds_bpermute_b32 v8, v8, v15
	s_mov_b32 s59, 0x42040000
	s_mov_b32 s33, 0x4e000000
	s_waitcnt lgkmcnt(0)
	v_fmac_f32_e32 v14, v2, v3
	ds_bpermute_b32 v2, v9, v14
	v_fmac_f32_e32 v8, v4, v5
	ds_bpermute_b32 v3, v9, v8
	v_cndmask_b32_e32 v4, v0, v10, vcc
	v_lshlrev_b32_e32 v4, 2, v4
	s_waitcnt lgkmcnt(1)
	v_add_f32_e32 v2, v14, v2
	ds_bpermute_b32 v5, v4, v2
	s_waitcnt lgkmcnt(1)
	v_add_f32_e32 v3, v8, v3
	ds_bpermute_b32 v4, v4, v3
	v_cmp_lt_i32_e32 vcc, v11, v7
	s_mov_b32 s61, -2.0
	s_waitcnt lgkmcnt(1)
	v_add_f32_e32 v2, v2, v5
	v_cndmask_b32_e32 v8, v0, v11, vcc
	v_lshlrev_b32_e32 v8, 2, v8
	s_waitcnt lgkmcnt(0)
	v_add_f32_e32 v3, v3, v4
	ds_bpermute_b32 v4, v8, v2
	ds_bpermute_b32 v5, v8, v3
	v_cmp_lt_i32_e32 vcc, v12, v7
	s_mov_b32 s65, 0xc1000000
	s_mov_b32 s67, 0xc1200000
	v_cndmask_b32_e32 v8, v0, v12, vcc
	v_lshlrev_b32_e32 v8, 2, v8
	s_waitcnt lgkmcnt(1)
	v_add_f32_e32 v2, v2, v4
	s_waitcnt lgkmcnt(0)
	v_add_f32_e32 v3, v3, v5
	ds_bpermute_b32 v4, v8, v2
	ds_bpermute_b32 v5, v8, v3
	v_cmp_lt_i32_e32 vcc, v13, v7
	s_mov_b32 s69, 0xc1800000
	s_mov_b32 s71, 0xc1900000
	v_cndmask_b32_e32 v0, v0, v13, vcc
	v_lshlrev_b32_e32 v0, 2, v0
	s_waitcnt lgkmcnt(1)
	v_add_f32_e32 v2, v2, v4
	s_waitcnt lgkmcnt(0)
	v_add_f32_e32 v3, v3, v5
	ds_bpermute_b32 v4, v0, v2
	ds_bpermute_b32 v0, v0, v3
	s_mov_b32 s73, 0xc1c00000
	s_mov_b32 s75, 0xc1d00000
	s_mov_b32 s77, 0xc2000000
	s_waitcnt lgkmcnt(1)
	v_add_f32_e32 v2, v2, v4
	s_waitcnt lgkmcnt(0)
	v_add_f32_e32 v0, v3, v0
	v_mul_f32_e32 v3, 0x3fb8aa3b, v2
	v_mul_f32_e32 v4, 0x3fb8aa3b, v0
	v_fma_f32 v5, v2, s2, -v3
	v_rndne_f32_e32 v7, v3
	v_fma_f32 v8, v0, s2, -v4
	v_rndne_f32_e32 v9, v4
	v_fmac_f32_e32 v5, 0x32a5705f, v2
	v_sub_f32_e32 v3, v3, v7
	v_fmac_f32_e32 v8, 0x32a5705f, v0
	v_sub_f32_e32 v4, v4, v9
	v_add_f32_e32 v3, v3, v5
	v_cvt_i32_f32_e32 v7, v7
	v_add_f32_e32 v4, v4, v8
	v_exp_f32_e32 v3, v3
	v_cvt_i32_f32_e32 v9, v9
	v_exp_f32_e32 v4, v4
	v_cmp_ngt_f32_e32 vcc, s1, v2
	v_ldexp_f32 v3, v3, v7
	s_mov_b32 s79, 0xc2080000
	v_ldexp_f32 v4, v4, v9
	v_cndmask_b32_e32 v3, 0, v3, vcc
	v_cmp_ngt_f32_e32 vcc, s1, v0
	s_mov_b32 s81, 0xc2200000
	s_mov_b32 s83, 0xc2280000
	v_cndmask_b32_e32 v4, 0, v4, vcc
	v_cmp_nlt_f32_e32 vcc, s0, v2
	s_mov_b32 s85, 0xc2400000
	s_mov_b32 s87, 0xc2480000
	v_cndmask_b32_e32 v2, v6, v3, vcc
	v_cmp_nlt_f32_e32 vcc, s0, v0
	s_mov_b32 s89, 0xc2600000
	s_mov_b32 s91, 0xc2680000
	v_cndmask_b32_e32 v0, v6, v4, vcc
	v_sub_f32_e32 v0, v2, v0
	v_add_f32_e32 v128, 0x3eb60549, v0
	v_mov_b32_e32 v129, v128
	v_mov_b32_e32 v150, 0x358637bd
	v_mov_b32_e32 v151, 1
	v_mov_b32_e32 v152, 0x42800000
	v_mov_b32_e32 v153, 0xff800000
	s_branch .LBB0_1475

; DI int ltid() { int x = threadIdx.x; asm volatile("" : "+v"(x)); return x; }
; DI int fetch_task(unsigned* ctr, char* smem) {
;   unsigned* slot = (unsigned*)(smem + SM_TASK);
;   __syncthreads();
;   if (ltid() == 0) *slot = atomicAdd(ctr, 1u);
;   __syncthreads();
;   return (int)*slot;
; }
; DI void diff_attn_phase(const Params& p, char* smem) {
;     ...
;     const int slot = fetch_task(p.ctr + 1, smem);
;     if (slot >= 2048) break;
;     const int tid = ltid(), lane = tid & 63, wid = tid >> 6, r = lane & 31, h = lane >> 5;
;     const int pair = slot >> 1, mm = (slot & 1) ? 0 : 1;
;     const int qt = 63 - (pair >> 4), bh = pair & 15;
;     const int b = bh >> 3, hd = bh & 7;
;     const int q0 = qt * 128 + wid * 32, tq = q0 + r;
;     const long tok = (long)b * SEQ + tq;
;     const float slope2 = exp2f(-(float)(hd + 1)) * LOG2E;
;     const int thi = ((qt * 128 + 127) >> 6) + 1;
;     const u16* vb_ = p.qkvz + (long)b * SEQ * LD + 2048 + hd * 128;
;     f32x16 ot[4];
;     float rl;
;     {
;       bf16x8 qf[4];
;       load_q(qf, p.qkvz + tok * LD + hd * 128 + mm * 64, h);
;       const u16* kb_ = p.qkvz + (long)b * SEQ * LD + 1024 + hd * 128 + mm * 64;
;       float m = 0.f, l = 0.f;
; #pragma unroll
;       for (int dc = 0; dc < 4; ++dc)
; #pragma unroll
;         for (int i = 0; i < 16; ++i) ot[dc][i] = 0.f;
;       const float qb = q_bound(qf, p.kmax2[128 + b * 64 + 16 + hd * 2 + mm]);
.LBB0_1475:
	v_mov_b32_e32 v0, v222
	s_barrier
	s_nop 0
	v_cmp_eq_u32_e32 vcc, 0, v0
	s_and_saveexec_b64 s[0:1], vcc
	s_cbranch_execz .LBB0_1479
	s_mov_b64 s[6:7], exec
	v_mbcnt_lo_u32_b32 v0, s6, 0
	v_mbcnt_hi_u32_b32 v0, s7, v0
	v_cmp_eq_u32_e32 vcc, 0, v0
	s_and_saveexec_b64 s[4:5], vcc
	s_cbranch_execz .LBB0_1478
	s_bcnt1_i32_b64 s2, s[6:7]
	v_readlane_b32 s8, v255, 14
	v_mov_b32_e32 v2, s2
	v_readlane_b32 s10, v255, 16
	v_readlane_b32 s11, v255, 17
	v_readlane_b32 s9, v255, 15
	s_nop 3
	s_cmp_eq_u32 s98, 0
	s_cbranch_scc1 .Lft_skip_diff
	global_atomic_add v2, v1, v2, s[10:11] offset:4 sc0
.Lft_skip_diff:
.LBB0_1478:
	s_or_b64 exec, exec, s[4:5]
	s_waitcnt vmcnt(0)
	v_readfirstlane_b32 s2, v2
	s_nop 1
	v_add_u32_e32 v0, s2, v0
	s_waitcnt lgkmcnt(0)
	v_add_u32_e32 v0, s99, v0
	s_cmp_eq_u32 s98, 0
	s_cbranch_scc0 .Lft_st_diff
	v_readlane_b32 s100, v255, 2
	s_nop 1
	v_mov_b32_e32 v0, s100
.Lft_st_diff:
	ds_write_b32 v148, v0
.LBB0_1479:
	s_or_b64 exec, exec, s[0:1]
	s_waitcnt lgkmcnt(0)
	s_barrier
	ds_read_b32 v0, v148
	s_mov_b32 s98, 1
	s_movk_i32 s0, 0x7ff
	s_waitcnt lgkmcnt(0)
	v_cmp_lt_i32_e32 vcc, s0, v0
	v_readfirstlane_b32 s2, v0
	s_mov_b64 s[0:1], -1
	s_cbranch_vccnz .LBB0_1474
	v_mov_b32_e32 v154, v222
	s_ashr_i32 s92, s2, 1
	s_lshl_b32 s0, s2, 2
	v_ashrrev_i32_e32 v0, 1, v154
	s_and_b32 s17, s92, 7
	s_and_b32 s4, s0, 0xffffff80
	v_and_b32_e32 v0, 0xffffffe0, v0
	v_subrev_u32_e32 v2, s4, v0
	s_add_i32 s0, s17, 1
	s_and_b32 s56, s2, 1
	s_bfe_u32 s16, s92, 0x10003
	v_add_u32_e32 v156, 0x1f80, v2
	v_cvt_f32_ubyte0_e32 v3, s0
	s_mov_b32 s0, 0x42fc0000
	s_xor_b32 s11, s56, 1
	v_and_or_b32 v134, v154, 31, v156
	s_lshl_b32 s2, s16, 13
	v_cmp_lt_f32_e32 vcc, s0, v3
	v_ashrrev_i32_e32 v135, 31, v134
	s_and_b64 s[0:1], vcc, exec
	v_lshl_add_u64 v[132:133], v[134:135], 0, s[2:3]
	s_cselect_b32 s1, 0xffffffc0, 0
	s_sub_i32 s0, 0x1fc0, s4
	s_lshl_b32 s2, s16, 26
	s_add_u32 s6, s62, s2
	v_lshlrev_b64 v[4:5], 13, v[132:133]
	s_addc_u32 s7, s63, 0
	v_lshl_add_u64 v[130:131], s[62:63], 0, v[4:5]
	s_lshl_b32 s2, s17, 8
	v_bfe_u32 v155, v154, 5, 1
	v_lshl_add_u64 v[4:5], v[130:131], 0, s[2:3]
	s_lshl_b32 s4, s11, 7
	s_mov_b32 s5, s3
	v_lshl_add_u64 v[4:5], v[4:5], 0, s[4:5]
	v_lshlrev_b32_e32 v0, 4, v155
	v_lshl_add_u64 v[4:5], v[4:5], 0, v[0:1]
	global_load_dwordx4 v[112:115], v[4:5], off
	global_load_dwordx4 v[116:119], v[4:5], off offset:32
	global_load_dwordx4 v[120:123], v[4:5], off offset:64
	global_load_dwordx4 v[124:127], v[4:5], off offset:96
	s_lshl_b32 s57, s17, 7
	s_add_u32 s8, s6, s2
	s_addc_u32 s9, s7, 0
	s_lshr_b32 s10, s0, 6
	s_add_u32 s6, s8, s4
	s_addc_u32 s7, s9, 0
	s_lshl_b32 s2, s16, 6
	s_lshl_b32 s4, s17, 1
	s_or_b32 s2, s2, s4
	s_or_b32 s2, s2, s11
	s_lshl_b32 s2, s2, 2
	v_readlane_b32 s16, v255, 14
	v_mov_b32_e32 v0, s2
	v_readlane_b32 s17, v255, 15
	v_cndmask_b32_e32 v6, 0, v152, vcc
	v_sub_f32_e32 v3, v6, v3
	s_mov_b32 s4, 0xf800000
	v_exp_f32_e32 v3, v3
	v_add_u32_e32 v157, 0x1f9f, v2
	global_load_dword v0, v0, s[16:17] offset:576
	s_add_i32 s24, s10, -1
	v_ldexp_f32 v3, v3, s1
	v_mul_f32_e32 v136, 0x3fb8aa3b, v3
	s_mov_b32 s1, 0x3f828f5c
	v_mov_b32_e32 v183, 0
	s_mov_b32 s2, 2
	s_mov_b32 s93, 0
	v_add_u32_e32 v171, 1, v134
	v_mov_b32_e32 v144, v136
	v_mov_b32_e32 v145, v136
	v_mov_b32_e32 v146, v136
	v_mov_b32_e32 v147, v136
	s_add_i32 s25, s10, 1
	s_mov_b32 s16, 0
	v_mov_b32_e32 v184, 0
	s_mov_b32 s17, 0
	v_mov_b32_e32 v80, 0
	v_mov_b32_e32 v81, v183
	v_mov_b32_e32 v82, v183
	v_mov_b32_e32 v83, v183
	v_mov_b32_e32 v84, v183
	v_mov_b32_e32 v85, v183
	v_mov_b32_e32 v86, v183
	v_mov_b32_e32 v87, v183
	v_mov_b32_e32 v88, v183
	v_mov_b32_e32 v89, v183
	v_mov_b32_e32 v90, v183
	v_mov_b32_e32 v91, v183
	v_mov_b32_e32 v92, v183
	v_mov_b32_e32 v93, v183
	v_mov_b32_e32 v94, v183
	v_mov_b32_e32 v95, v183
	v_mov_b32_e32 v96, v183
	v_mov_b32_e32 v97, v183
	v_mov_b32_e32 v98, v183
	v_mov_b32_e32 v99, v183
	v_mov_b32_e32 v100, v183
	v_mov_b32_e32 v101, v183
	v_mov_b32_e32 v102, v183
	v_mov_b32_e32 v103, v183
	v_mov_b32_e32 v104, v183
	v_mov_b32_e32 v105, v183
	v_mov_b32_e32 v106, v183
	v_mov_b32_e32 v107, v183
	v_mov_b32_e32 v108, v183
	v_mov_b32_e32 v109, v183
	v_mov_b32_e32 v110, v183
	v_mov_b32_e32 v111, v183
	v_readlane_b32 s18, v255, 16
	v_readlane_b32 s19, v255, 17
	s_waitcnt vmcnt(0)
	v_and_b32_e32 v5, 0xffff0000, v112
	v_lshlrev_b32_e32 v4, 16, v112
	v_mul_f32_e32 v5, v5, v5
	v_lshlrev_b32_e32 v6, 16, v113
	v_fmac_f32_e32 v5, v4, v4
	v_and_b32_e32 v7, 0xffff0000, v113
	v_fmac_f32_e32 v5, v6, v6
	v_lshlrev_b32_e32 v8, 16, v114
	v_fmac_f32_e32 v5, v7, v7
	v_and_b32_e32 v9, 0xffff0000, v114
	v_fmac_f32_e32 v5, v8, v8
	v_lshlrev_b32_e32 v10, 16, v115
	v_fmac_f32_e32 v5, v9, v9
	v_and_b32_e32 v11, 0xffff0000, v115
	v_fmac_f32_e32 v5, v10, v10
	s_waitcnt vmcnt(3)
	v_lshlrev_b32_e32 v12, 16, v116
	v_fmac_f32_e32 v5, v11, v11
	v_and_b32_e32 v13, 0xffff0000, v116
	v_fmac_f32_e32 v5, v12, v12
	v_lshlrev_b32_e32 v14, 16, v117
	v_fmac_f32_e32 v5, v13, v13
	v_and_b32_e32 v15, 0xffff0000, v117
	v_fmac_f32_e32 v5, v14, v14
	v_lshlrev_b32_e32 v16, 16, v118
	v_fmac_f32_e32 v5, v15, v15
	v_and_b32_e32 v17, 0xffff0000, v118
	v_fmac_f32_e32 v5, v16, v16
	v_lshlrev_b32_e32 v18, 16, v119
	v_fmac_f32_e32 v5, v17, v17
	v_and_b32_e32 v19, 0xffff0000, v119
	v_fmac_f32_e32 v5, v18, v18
	s_waitcnt vmcnt(2)
	v_lshlrev_b32_e32 v20, 16, v120
	v_fmac_f32_e32 v5, v19, v19
	v_and_b32_e32 v21, 0xffff0000, v120
	v_fmac_f32_e32 v5, v20, v20
	v_lshlrev_b32_e32 v22, 16, v121
	v_fmac_f32_e32 v5, v21, v21
	v_and_b32_e32 v23, 0xffff0000, v121
	v_fmac_f32_e32 v5, v22, v22
	v_lshlrev_b32_e32 v24, 16, v122
	v_fmac_f32_e32 v5, v23, v23
	v_and_b32_e32 v25, 0xffff0000, v122
	v_fmac_f32_e32 v5, v24, v24
	v_lshlrev_b32_e32 v26, 16, v123
	v_fmac_f32_e32 v5, v25, v25
	v_and_b32_e32 v27, 0xffff0000, v123
	v_fmac_f32_e32 v5, v26, v26
	s_waitcnt vmcnt(1)
	v_lshlrev_b32_e32 v28, 16, v124
	v_fmac_f32_e32 v5, v27, v27
	v_and_b32_e32 v29, 0xffff0000, v124
	v_fmac_f32_e32 v5, v28, v28
	v_lshlrev_b32_e32 v30, 16, v125
	v_fmac_f32_e32 v5, v29, v29
	v_and_b32_e32 v31, 0xffff0000, v125
	v_fmac_f32_e32 v5, v30, v30
	v_lshlrev_b32_e32 v32, 16, v126
	v_fmac_f32_e32 v5, v31, v31
	v_and_b32_e32 v33, 0xffff0000, v126
	v_fmac_f32_e32 v5, v32, v32
	v_lshlrev_b32_e32 v34, 16, v127
	v_fmac_f32_e32 v5, v33, v33
	v_and_b32_e32 v35, 0xffff0000, v127
	v_fmac_f32_e32 v5, v34, v34
	v_fmac_f32_e32 v5, v35, v35
	v_mov_b32_e32 v4, v5
	s_nop 1
	v_permlane32_swap_b32_e32 v5, v4
	v_add_f32_e32 v4, v5, v4
	s_waitcnt vmcnt(0)
	v_mul_f32_e32 v0, v0, v4
	v_mul_f32_e32 v4, 0x4f800000, v0
	v_cmp_gt_f32_e32 vcc, s4, v0
	s_nop 1
	v_cndmask_b32_e32 v0, v0, v4, vcc
	v_sqrt_f32_e32 v4, v0
	s_nop 0
	v_add_u32_e32 v3, -1, v4
	v_add_u32_e32 v5, 1, v4
	v_fma_f32 v6, -v3, v4, v0
	v_fma_f32 v7, -v5, v4, v0
	v_cmp_ge_f32_e64 s[4:5], 0, v6
	v_mov_b32_e32 v6, v222
	s_waitcnt lgkmcnt(0)
	s_barrier
; #define LAS __attribute__((address_space(3)))
; DI int ltid() { int x = threadIdx.x; asm volatile("" : "+v"(x)); return x; }
; #define RAW_BARRIER() do { asm volatile("s_waitcnt lgkmcnt(0)" ::: "memory"); __builtin_amdgcn_s_barrier(); } while (0)
; template <int DV, bool WITH_V>
; DI void kv_issue(char* smem, int stage, const u16* kbase, long kpitch, const u16* vbase, long vpitch, int t, int lane, int wid) {
;   char* sb = smem + stage * Ring<DV>::STAGE;
;   {
;     const int lr = lane >> 3;
; #pragma unroll
;     for (int j = 0; j < 2; ++j) {
;       const int q = wid * 2 + j, row = q * 8 + lr;
;       const int cc = (lane & 7) ^ ((row >> 1) & 7);
;       __builtin_amdgcn_global_load_lds((const unsigned*)(kbase + (long)(t * 64 + row) * kpitch + cc * 8), (LAS unsigned*)(sb + q * 1024), 16, 0, 0);
;     }
;   }
;   if (WITH_V) {
;     if (DV == 128) {
;       const int lr = lane >> 4, cc = (lane & 15) ^ (lr << 2);
; #pragma unroll
;       for (int j = 0; j < 4; ++j) {
;         const int q = wid * 4 + j, row = q * 4 + lr;
;         __builtin_amdgcn_global_load_lds((const unsigned*)(vbase + (long)(t * 64 + row) * vpitch + cc * 8), (LAS unsigned*)(sb + 8192 + q * 1024), 16, 0, 0);
;       }
;     } else {
;       const int lr = lane >> 3, cc = (lane & 7) ^ (((lr >> 1) & 1) << 2);
; #pragma unroll
;       for (int j = 0; j < 2; ++j) {
;         const int q = wid * 2 + j, row = q * 8 + lr;
;         __builtin_amdgcn_global_load_lds((const unsigned*)(vbase + (long)(t * 64 + row) * vpitch + cc * 8), (LAS unsigned*)(sb + 8192 + q * 1024), 16, 0, 0);
;       }
;     }
;   }
; template <int DV, bool SEL, bool TERM> ...
;     ...
;   const int tid = ltid(), lane = tid & 63, wid = tid >> 6, r = lane & 31, h = lane >> 5;
;   unsigned* flags = (unsigned*)(smem + SM_FLAG);
;   int foff[4];
;   make_foff(foff, r, h);
;   unsigned done = 0u;
;   const float sk = slope2 * (float)kp_mul;
;   RAW_BARRIER();
;   int t = prev_active(thi - 1, tlo, um);
;   int t1 = (t >= tlo) ? prev_active(t - 1, tlo, um) : t;
;   if (t >= tlo) kv_issue<DV, true>(smem, 0, kbase, kpitch, vbase, vpitch, t, lane, wid);
;   if (t1 >= tlo) kv_issue<DV, true>(smem, 1, kbase, kpitch, vbase, vpitch, t1, lane, wid);
	v_cndmask_b32_e64 v3, v4, v3, s[4:5]
	v_cmp_lt_f32_e64 s[4:5], 0, v7
	v_ashrrev_i32_e32 v8, 6, v6
	v_bfe_u32 v9, v6, 5, 1
	v_cndmask_b32_e64 v3, v3, v5, s[4:5]
	v_mul_f32_e32 v4, 0x37800000, v3
	v_cndmask_b32_e32 v3, v3, v4, vcc
	v_cmp_class_f32_e32 vcc, v0, v149
	v_bfe_u32 v2, v6, 1, 3
	v_bfe_u32 v15, v6, 3, 3
	v_cndmask_b32_e32 v0, v3, v0, vcc
	v_fma_f32 v135, v0, s1, 1.0
	v_lshlrev_b32_e32 v0, 7, v6
	v_bitop3_b32 v12, v9, v2, 2 bitop3:0x36
	v_bitop3_b32 v13, v9, v2, 4 bitop3:0x36
	v_bitop3_b32 v14, v9, v2, 6 bitop3:0x36
	v_lshlrev_b32_e32 v158, 4, v8
	v_or_b32_e32 v2, s0, v15
	v_and_b32_e32 v10, 0xf80, v0
	v_lshrrev_b32_e32 v0, 1, v6
	v_bfe_u32 v159, v6, 4, 2
	v_add_u32_e32 v2, v2, v158
	v_bitop3_b32 v11, v9, v0, 7 bitop3:0x78
	v_xor_b32_e32 v0, v159, v6
	v_ashrrev_i32_e32 v3, 31, v2
	v_lshlrev_b64 v[2:3], 13, v[2:3]
	v_lshlrev_b32_e32 v0, 4, v0
	v_lshl_add_u64 v[2:3], s[6:7], 0, v[2:3]
	v_and_b32_e32 v0, 0x70, v0
	v_lshlrev_b32_e32 v16, 11, v8
	v_lshl_add_u64 v[2:3], v[2:3], 0, v[0:1]
	v_readfirstlane_b32 s1, v16
	v_lshl_or_b32 v17, v8, 1, 1
	v_lshl_add_u64 v[2:3], v[2:3], 0, s[12:13]
	s_mov_b32 m0, s1
	v_lshl_or_b32 v160, v17, 3, v15
	global_load_lds_dwordx4 v[2:3], off
	v_lshrrev_b32_e32 v2, 1, v160
	v_xor_b32_e32 v4, v2, v6
	v_add_u32_e32 v2, s0, v160
	v_ashrrev_i32_e32 v3, 31, v2
	v_lshlrev_b64 v[2:3], 13, v[2:3]
	v_lshlrev_b32_e32 v4, 4, v4
	v_lshl_add_u64 v[2:3], s[6:7], 0, v[2:3]
	v_and_b32_e32 v4, 0x70, v4
	v_mov_b32_e32 v5, v1
	v_lshlrev_b32_e32 v17, 10, v17
	v_lshl_add_u64 v[2:3], v[2:3], 0, v[4:5]
	v_readfirstlane_b32 s1, v17
	v_lshl_add_u64 v[2:3], v[2:3], 0, s[12:13]
	s_mov_b32 m0, s1
	v_or_b32_e32 v19, s0, v159
	global_load_lds_dwordx4 v[2:3], off
	v_lshlrev_b32_e32 v2, 4, v6
	v_lshlrev_b32_e32 v3, 6, v159
	s_movk_i32 s0, 0xf0
	v_bitop3_b32 v2, v3, v2, s0 bitop3:0x78
	v_mov_b32_e32 v3, v1
	v_lshl_add_u64 v[2:3], s[8:9], 0, v[2:3]
	s_mov_b64 s[0:1], 0x1000
	v_lshl_add_u64 v[138:139], v[2:3], 0, s[0:1]
	v_add_u32_e32 v2, v19, v158
	v_add_u32_e32 v21, v16, v16
	v_lshlrev_b32_e32 v18, 2, v8
	v_ashrrev_i32_e32 v3, 31, v2
	v_add_u32_e32 v22, 0x2000, v21
	v_lshlrev_b64 v[2:3], 13, v[2:3]
	v_readfirstlane_b32 s0, v22
	v_or_b32_e32 v22, 1, v18
	v_lshl_add_u64 v[2:3], v[138:139], 0, v[2:3]
	s_mov_b32 m0, s0
	v_lshlrev_b32_e32 v161, 2, v22
	global_load_lds_dwordx4 v[2:3], off
	v_add_u32_e32 v2, v161, v19
	v_lshlrev_b32_e32 v22, 10, v22
	v_ashrrev_i32_e32 v3, 31, v2
	v_add_u32_e32 v23, 0x2000, v22
	v_lshlrev_b64 v[2:3], 13, v[2:3]
	v_readfirstlane_b32 s0, v23
	v_or_b32_e32 v23, 2, v18
	v_lshl_add_u64 v[2:3], v[138:139], 0, v[2:3]
	s_mov_b32 m0, s0
	v_lshlrev_b32_e32 v162, 2, v23
	global_load_lds_dwordx4 v[2:3], off
	v_add_u32_e32 v2, v162, v19
	v_lshlrev_b32_e32 v23, 10, v23
	v_ashrrev_i32_e32 v3, 31, v2
	v_add_u32_e32 v24, 0x2000, v23
	v_lshlrev_b64 v[2:3], 13, v[2:3]
	v_readfirstlane_b32 s0, v24
	v_or_b32_e32 v24, 3, v18
	v_lshl_add_u64 v[2:3], v[138:139], 0, v[2:3]
	s_mov_b32 m0, s0
	v_lshlrev_b32_e32 v163, 2, v24
	global_load_lds_dwordx4 v[2:3], off
	v_add_u32_e32 v2, v163, v19
	v_lshlrev_b32_e32 v19, 10, v24
	v_ashrrev_i32_e32 v3, 31, v2
	v_add_u32_e32 v24, 0x2000, v19
	v_lshlrev_b64 v[2:3], 13, v[2:3]
	v_readfirstlane_b32 s0, v24
	v_lshl_add_u64 v[2:3], v[138:139], 0, v[2:3]
	s_mov_b32 m0, s0
	s_lshl_b32 s0, s24, 6
	global_load_lds_dwordx4 v[2:3], off
	v_or_b32_e32 v2, s0, v15
	v_add_u32_e32 v2, v2, v158
	v_ashrrev_i32_e32 v3, 31, v2
	v_lshlrev_b64 v[2:3], 13, v[2:3]
	v_lshl_add_u64 v[2:3], s[6:7], 0, v[2:3]
	v_add_u32_e32 v24, 0x6000, v16
	v_lshl_add_u64 v[2:3], v[2:3], 0, v[0:1]
	v_readfirstlane_b32 s1, v24
	v_lshl_add_u64 v[2:3], v[2:3], 0, s[12:13]
	s_mov_b32 m0, s1
	v_add_u32_e32 v17, 0x6000, v17
	global_load_lds_dwordx4 v[2:3], off
	v_add_u32_e32 v2, s0, v160
	v_ashrrev_i32_e32 v3, 31, v2
	v_lshlrev_b64 v[2:3], 13, v[2:3]
	v_lshl_add_u64 v[2:3], s[6:7], 0, v[2:3]
	v_lshl_add_u64 v[2:3], v[2:3], 0, v[4:5]
	v_readfirstlane_b32 s1, v17
	v_lshl_add_u64 v[2:3], v[2:3], 0, s[12:13]
	s_mov_b32 m0, s1
	v_or_b32_e32 v17, s0, v159
	global_load_lds_dwordx4 v[2:3], off
	v_add_u32_e32 v2, v17, v158
	v_ashrrev_i32_e32 v3, 31, v2
	v_add_u32_e32 v21, 0x8000, v21
	v_lshlrev_b64 v[2:3], 13, v[2:3]
	v_readfirstlane_b32 s0, v21
	v_lshl_add_u64 v[2:3], v[138:139], 0, v[2:3]
; #define LAS __attribute__((address_space(3)))
; template <int DV, bool WITH_V>
; DI void kv_issue(char* smem, int stage, const u16* kbase, long kpitch, const u16* vbase, long vpitch, int t, int lane, int wid) {
;   char* sb = smem + stage * Ring<DV>::STAGE;
;   {
;     const int lr = lane >> 3;
; #pragma unroll
;     for (int j = 0; j < 2; ++j) {
;       const int q = wid * 2 + j, row = q * 8 + lr;
;       const int cc = (lane & 7) ^ ((row >> 1) & 7);
;       __builtin_amdgcn_global_load_lds((const unsigned*)(kbase + (long)(t * 64 + row) * kpitch + cc * 8), (LAS unsigned*)(sb + q * 1024), 16, 0, 0);
;     }
;   }
;   if (WITH_V) {
;     if (DV == 128) {
;       const int lr = lane >> 4, cc = (lane & 15) ^ (lr << 2);
; #pragma unroll
;       for (int j = 0; j < 4; ++j) {
;         const int q = wid * 4 + j, row = q * 4 + lr;
;         __builtin_amdgcn_global_load_lds((const unsigned*)(vbase + (long)(t * 64 + row) * vpitch + cc * 8), (LAS unsigned*)(sb + 8192 + q * 1024), 16, 0, 0);
;       }
;     } else {
;       const int lr = lane >> 3, cc = (lane & 7) ^ (((lr >> 1) & 1) << 2);
; #pragma unroll
;       for (int j = 0; j < 2; ++j) {
;         const int q = wid * 2 + j, row = q * 8 + lr;
;         __builtin_amdgcn_global_load_lds((const unsigned*)(vbase + (long)(t * 64 + row) * vpitch + cc * 8), (LAS unsigned*)(sb + 8192 + q * 1024), 16, 0, 0);
;       }
;     }
;   }
; template <int DV>
; DI void pv_tile(f32x16 (&ot)[DV / 32], const bf16x8 (&pk)[2][2], char* sb, int lane) {
;   constexpr int VP = 2 * DV, NDC = DV / 32;
;   const int h = lane >> 5, i16 = lane & 15, qq = i16 >> 2, pp = i16 & 3, blk = (lane >> 4) & 1;
;   const int qx = (DV == 128) ? qq : (qq >> 1);
;   const unsigned vb = (unsigned)(size_t)(sb + 8192) + (4 * h + qq) * VP + 32 * blk + 8 * pp;
;   unsigned a[NDC];
; #pragma unroll
;   for (int dc = 0; dc < NDC; ++dc) a[dc] = vb + ((dc ^ qx) << 6);
;   s16x4 f0[NDC][2], f1[NDC][2];
	s_mov_b32 m0, s0
	v_add_u32_e32 v21, 0x8000, v22
	global_load_lds_dwordx4 v[2:3], off
	v_add_u32_e32 v2, v161, v17
	v_ashrrev_i32_e32 v3, 31, v2
	v_lshlrev_b64 v[2:3], 13, v[2:3]
	v_readfirstlane_b32 s0, v21
	v_lshl_add_u64 v[2:3], v[138:139], 0, v[2:3]
	s_mov_b32 m0, s0
	v_add_u32_e32 v21, 0x8000, v23
	global_load_lds_dwordx4 v[2:3], off
	v_add_u32_e32 v2, v162, v17
	v_ashrrev_i32_e32 v3, 31, v2
	v_lshlrev_b64 v[2:3], 13, v[2:3]
	v_readfirstlane_b32 s0, v21
	v_lshl_add_u64 v[2:3], v[138:139], 0, v[2:3]
	s_mov_b32 m0, s0
	v_lshl_add_u64 v[140:141], s[6:7], 0, v[0:1]
	global_load_lds_dwordx4 v[2:3], off
	v_add_u32_e32 v2, v163, v17
	v_ashrrev_i32_e32 v3, 31, v2
	v_add_u32_e32 v17, 0x8000, v19
	v_lshlrev_b64 v[2:3], 13, v[2:3]
	v_readfirstlane_b32 s0, v17
	v_lshl_add_u64 v[2:3], v[138:139], 0, v[2:3]
	s_mov_b32 m0, s0
	v_bfe_u32 v0, v6, 2, 2
	global_load_lds_dwordx4 v[2:3], off
	v_lshrrev_b32_e32 v2, 3, v6
	v_lshlrev_b32_e32 v20, 3, v6
	v_and_or_b32 v2, v2, 4, v0
	v_lshlrev_b32_e32 v3, 1, v6
	v_and_b32_e32 v7, 63, v6
	v_lshlrev_b32_e32 v8, 12, v8
	v_or_b32_e32 v165, v158, v15
	v_lshl_add_u64 v[142:143], s[6:7], 0, v[4:5]
	v_lshlrev_b32_e32 v2, 8, v2
	v_and_b32_e32 v3, 32, v3
	v_and_b32_e32 v4, 24, v20
	v_lshl_or_b32 v179, v14, 4, v10
	v_mov_b32_e32 v14, v1
	v_mov_b32_e32 v15, v1
	v_add_u32_e32 v164, 0x12000, v18
	v_cmp_eq_u32_e64 s[4:5], 0, v7
	v_or3_b32 v166, v4, v3, v2
	v_lshlrev_b32_e32 v167, 6, v0
	v_lshlrev_b32_e32 v172, 2, v9
	v_add_u32_e32 v173, 0xec00, v8
	v_add_u32_e32 v174, 0xe800, v8
	v_add_u32_e32 v175, 0xe400, v8
	v_add_u32_e32 v176, 0xe000, v8
	v_add_u32_e32 v177, 0xc400, v16
	v_add_u32_e32 v178, 0xc000, v16
	v_lshl_or_b32 v180, v11, 4, v10
	v_lshl_or_b32 v181, v13, 4, v10
	v_lshl_or_b32 v182, v12, 4, v10
	v_mov_b32_e32 v0, v1
	v_mov_b32_e32 v2, v1
	v_mov_b32_e32 v3, v1
	v_mov_b32_e32 v4, v1
	v_mov_b32_e32 v6, v1
	v_mov_b32_e32 v7, v1
	v_mov_b32_e32 v8, v1
	v_mov_b32_e32 v9, v1
	v_mov_b32_e32 v10, v1
	v_mov_b32_e32 v11, v1
	v_mov_b32_e32 v12, v1
	v_mov_b32_e32 v13, v1
	v_mov_b64_e32 v[30:31], v[14:15]
	v_mov_b64_e32 v[46:47], v[14:15]
	v_mov_b64_e32 v[62:63], v[14:15]
	v_mov_b64_e32 v[78:79], v[14:15]
	v_xor_b32_e32 v168, 64, v167
	v_xor_b32_e32 v169, 0x80, v167
	v_xor_b32_e32 v170, 0xc0, v167
	v_mov_b64_e32 v[28:29], v[12:13]
	v_mov_b64_e32 v[26:27], v[10:11]
	v_mov_b64_e32 v[24:25], v[8:9]
	v_mov_b64_e32 v[22:23], v[6:7]
	v_mov_b64_e32 v[20:21], v[4:5]
	v_mov_b64_e32 v[18:19], v[2:3]
	v_mov_b64_e32 v[16:17], v[0:1]
	v_mov_b64_e32 v[44:45], v[12:13]
	v_mov_b64_e32 v[42:43], v[10:11]
	v_mov_b64_e32 v[40:41], v[8:9]
	v_mov_b64_e32 v[38:39], v[6:7]
	v_mov_b64_e32 v[36:37], v[4:5]
	v_mov_b64_e32 v[34:35], v[2:3]
	v_mov_b64_e32 v[32:33], v[0:1]
	v_mov_b64_e32 v[60:61], v[12:13]
	v_mov_b64_e32 v[58:59], v[10:11]
	v_mov_b64_e32 v[56:57], v[8:9]
	v_mov_b64_e32 v[54:55], v[6:7]
	v_mov_b64_e32 v[52:53], v[4:5]
	v_mov_b64_e32 v[50:51], v[2:3]
	v_mov_b64_e32 v[48:49], v[0:1]
	v_mov_b64_e32 v[76:77], v[12:13]
	v_mov_b64_e32 v[74:75], v[10:11]
	v_mov_b64_e32 v[72:73], v[8:9]
	v_mov_b64_e32 v[70:71], v[6:7]
	v_mov_b64_e32 v[68:69], v[4:5]
	v_mov_b64_e32 v[66:67], v[2:3]
	v_mov_b64_e32 v[64:65], v[0:1]
	v_mov_b32_e32 v6, 0
	v_mov_b32_e32 v224, v165
	v_ashrrev_i32_e32 v225, 31, v224
	v_lshlrev_b64 v[224:225], 13, v[224:225]
	v_lshl_add_u64 v[224:225], v[140:141], 0, v[224:225]
	v_lshl_add_u64 v[224:225], v[224:225], 0, s[12:13]
	v_mov_b32_e32 v226, v160
	v_ashrrev_i32_e32 v227, 31, v226
	v_lshlrev_b64 v[226:227], 13, v[226:227]
	v_lshl_add_u64 v[226:227], v[142:143], 0, v[226:227]
	v_lshl_add_u64 v[226:227], v[226:227], 0, s[12:13]
	v_add_u32_e32 v228, v159, v158
	v_ashrrev_i32_e32 v229, 31, v228
	v_lshlrev_b64 v[228:229], 13, v[228:229]
	v_lshl_add_u64 v[228:229], v[138:139], 0, v[228:229]
	v_add_u32_e32 v230, v159, v161
	v_ashrrev_i32_e32 v231, 31, v230
	v_lshlrev_b64 v[230:231], 13, v[230:231]
	v_lshl_add_u64 v[230:231], v[138:139], 0, v[230:231]
	v_add_u32_e32 v232, v159, v162
	v_ashrrev_i32_e32 v233, 31, v232
	v_lshlrev_b64 v[232:233], 13, v[232:233]
	v_lshl_add_u64 v[232:233], v[138:139], 0, v[232:233]
	v_add_u32_e32 v234, v159, v163
	v_ashrrev_i32_e32 v235, 31, v234
	v_lshlrev_b64 v[234:235], 13, v[234:235]
	v_lshl_add_u64 v[234:235], v[138:139], 0, v[234:235]

; template <int DV, bool SEL, bool TERM> ...
;     ...
;       for (int kb = 0; kb < 2; ++kb)
; #pragma unroll
;         for (int i = 0; i < 16; ++i) st[kb][i] = __builtin_fmaf(sk, (float)(kb * 32 + (i & 3) + 8 * (i >> 2)), tb);
; DI void dil1_attn_phase(const Params& p, char* smem) {
;     ...
;   for (;;) {
;     const int task = fetch_task(p.ctr + 4, smem);
;     if (task >= 1024) break;
.LBB0_1985:
	s_mov_b32 s98, 0
	s_load_dword s99, s[56:57], 0x170
	s_load_dwordx4 s[12:15], s[56:57], 0x108
	s_load_dwordx2 s[2:3], s[56:57], 0x130
	s_mov_b32 s22, 2.0
	s_mov_b32 s24, 0x41000000
	s_mov_b32 s26, 0x41200000
	s_mov_b32 s28, 0x41800000
	s_mov_b32 s30, 0x41900000
	s_mov_b32 s34, 0x41c00000
	s_mov_b32 s36, 0x41d00000
	s_mov_b32 s38, 0x42680000
	s_mov_b32 s40, 0x42600000
	s_mov_b32 s42, 0x42480000
	s_mov_b32 s44, 0x42400000
	s_mov_b32 s46, 0x42280000
	s_mov_b32 s48, 0x42200000
	s_mov_b32 s50, 0x42080000
	s_mov_b32 s52, 0x42000000
	s_mov_b32 s54, -1.0
	s_mov_b32 s58, 0xc0400000
	s_mov_b32 s60, 0xc1100000
	s_mov_b32 s62, 0xc1300000
	s_mov_b32 s64, 0xc1880000
	s_mov_b32 s66, 0xc1980000
	s_mov_b32 s68, 0xc1c80000
	s_mov_b32 s70, 0xc1d80000
	s_mov_b32 s72, 0xc2040000
	s_mov_b32 s74, 0xc20c0000
	s_mov_b32 s76, 0xc2240000
	s_mov_b32 s78, 0xc22c0000
	s_mov_b32 s80, 0xc2440000
	s_mov_b32 s82, 0xc24c0000
	s_mov_b32 s84, 0xc2640000
	s_mov_b32 s11, 0
	s_waitcnt vmcnt(0)
	v_mov_b32_e32 v1, 0
	v_mov_b32_e32 v144, 0x12020
	s_movk_i32 s33, 0x1c00
	s_mov_b64 s[18:19], 0x600
	s_movk_i32 s56, 0xf0
	s_mov_b64 s[20:21], 0xc00
	s_mov_b32 s57, 0x41400000
	s_movk_i32 s90, 0x81
	s_mov_b32 s23, 0x40400000
	s_mov_b32 s25, 0x41100000
	s_mov_b32 s27, 0x41300000
	s_mov_b32 s29, 0x41880000
	s_mov_b32 s31, 0x41980000
	s_mov_b32 s35, 0x41c80000
	s_mov_b32 s37, 0x41d80000
	s_mov_b32 s39, 0x426c0000
	s_mov_b32 s41, 0x42640000
	s_mov_b32 s43, 0x424c0000
	s_mov_b32 s45, 0x42440000
	s_mov_b32 s47, 0x422c0000
	s_mov_b32 s49, 0x42240000
	s_mov_b32 s51, 0x420c0000
	s_mov_b32 s53, 0x42040000
	s_mov_b32 s55, -2.0
	s_mov_b32 s91, 0x43010000
	s_mov_b32 s59, 0xc1000000
	s_mov_b32 s61, 0xc1200000
	s_mov_b32 s63, 0xc1800000
	s_mov_b32 s65, 0xc1900000
	s_mov_b32 s67, 0xc1c00000
	s_mov_b32 s69, 0xc1d00000
	s_mov_b32 s71, 0xc2000000
	s_mov_b32 s73, 0xc2080000
	s_mov_b32 s75, 0xc2200000
	s_mov_b32 s77, 0xc2280000
	s_mov_b32 s79, 0xc2400000
	s_mov_b32 s81, 0xc2480000
	s_mov_b32 s83, 0xc2600000
	s_mov_b32 s85, 0xc2680000
	v_mov_b32_e32 v145, 0x2000
	v_mov_b32_e32 v146, 0x6000
	v_mov_b32_e32 v147, 0x8000
	v_mov_b32_e32 v148, 0x42800000
	v_mov_b32_e32 v149, 0xff800000
	s_branch .LBB0_1988

; DI int ltid() { int x = threadIdx.x; asm volatile("" : "+v"(x)); return x; }
; DI int fetch_task(unsigned* ctr, char* smem) {
;   unsigned* slot = (unsigned*)(smem + SM_TASK);
;   __syncthreads();
;   if (ltid() == 0) *slot = atomicAdd(ctr, 1u);
;   __syncthreads();
;   return (int)*slot;
; }
.LBB0_1988:
	v_mov_b32_e32 v0, v222
	s_waitcnt lgkmcnt(0)
	s_barrier
	s_nop 0
	v_cmp_eq_u32_e32 vcc, 0, v0
	s_and_saveexec_b64 s[0:1], vcc
	s_cbranch_execz .LBB0_1992
	s_mov_b64 s[6:7], exec
	v_mbcnt_lo_u32_b32 v0, s6, 0
	v_mbcnt_hi_u32_b32 v0, s7, v0
	v_cmp_eq_u32_e32 vcc, 0, v0
	s_and_saveexec_b64 s[4:5], vcc
	s_cbranch_execz .LBB0_1991
	s_bcnt1_i32_b64 s6, s[6:7]
	v_mov_b32_e32 v2, s6
	s_cmp_eq_u32 s98, 0
	s_cbranch_scc1 .Lft_skip_dil1
	global_atomic_add v2, v1, v2, s[12:13] offset:16 sc0

; DI int ltid() { int x = threadIdx.x; asm volatile("" : "+v"(x)); return x; }
; DI int fetch_task(unsigned* ctr, char* smem) {
;   unsigned* slot = (unsigned*)(smem + SM_TASK);
;   __syncthreads();
;   if (ltid() == 0) *slot = atomicAdd(ctr, 1u);
;   __syncthreads();
;   return (int)*slot;
; }
; DI void dil1_attn_phase(const Params& p, char* smem) {
;     ...
;     const int task = fetch_task(p.ctr + 4, smem);
;     if (task >= 1024) break;
;     const int tid = ltid(), lane = tid & 63, wid = tid >> 6, r = lane & 31, h = lane >> 5;
;     const int half = task & 1, hg = (task >> 1) & 3, b = (task >> 3) & 1, qb128 = task >> 4;
;     const int q0 = qb128 * 128 + wid * 32, pos = q0 + r;
;     const long tok = (long)b * SEQ + pos;
;     f32x16 ot[4];
;     float m = 0.f, l = 0.f;
; #pragma unroll
;     for (int dc = 0; dc < 4; ++dc)
; #pragma unroll
;       for (int i = 0; i < 16; ++i) ot[dc][i] = 0.f;
;     const float slope2 = exp2f(-8.f * (float)(hg + 1) / 12.f) * LOG2E;
;     bf16x8 qf[4];
;     load_q(qf, p.qkvz + tok * LD + hg * 64, h);
;     const u16* kb_ = p.qkvz + (long)b * SEQ * LD + 768 + hg * 64;
;     const u16* vb_ = p.qkvz + (long)b * SEQ * LD + 1536 + hg * 256 + half * 128;
;     const int g0 = qb128 * 128;
;     const int tlo = (g0 - 128) > 0 ? ((g0 - 128) >> 6) : 0, thi = ((g0 + 127) >> 6) + 1;
;     flash_pass<128, false, false>(smem, kb_, LD, vb_, LD, tlo, thi, nullptr, qf, pos, 1, 129, slope2, q0, q0 + 31, nullptr, 0.f, ot, m, l);
.Lft_st_dil1:
	ds_write_b32 v144, v0
.LBB0_1992:
	s_or_b64 exec, exec, s[0:1]
	s_waitcnt lgkmcnt(0)
	s_barrier
	ds_read_b32 v0, v144
	s_mov_b32 s98, 1
	s_movk_i32 s0, 0x3ff
	s_waitcnt lgkmcnt(0)
	v_cmp_lt_i32_e32 vcc, s0, v0
	v_readfirstlane_b32 s8, v0
	s_mov_b64 s[0:1], -1
	s_cbranch_vccnz .LBB0_1987
	v_mov_b32_e32 v0, v222
	s_lshl_b32 s0, s8, 3
	v_ashrrev_i32_e32 v2, 1, v0
	s_and_b32 s9, s0, 0xffffff80
	v_and_b32_e32 v2, 0xffffffe0, v2
	v_add_u32_e32 v151, s9, v2
	v_and_or_b32 v130, v0, 31, v151
	s_lshl_b32 s0, s8, 10
	s_and_b32 s10, s0, 0x2000
	v_ashrrev_i32_e32 v131, 31, v130
	v_lshl_add_u64 v[128:129], v[130:131], 0, s[10:11]
	v_mov_b64_e32 v[2:3], s[2:3]
	s_bfe_u32 s92, s8, 0x20001
	v_mad_u64_u32 v[2:3], s[0:1], v128, s33, v[2:3]
	v_bfe_u32 v150, v0, 5, 1
	v_mad_i32_i24 v3, v129, s33, v3
	s_lshl_b32 s0, s92, 7
	s_mov_b32 s1, s11
	v_lshl_add_u64 v[2:3], v[2:3], 0, s[0:1]
	v_lshlrev_b32_e32 v0, 4, v150
	v_lshl_add_u64 v[2:3], v[2:3], 0, v[0:1]
	global_load_dwordx4 v[112:115], v[2:3], off
	global_load_dwordx4 v[116:119], v[2:3], off offset:32
	global_load_dwordx4 v[120:123], v[2:3], off offset:64
	global_load_dwordx4 v[124:127], v[2:3], off offset:96
	s_and_b32 s93, s8, 1
	s_mul_i32 s1, s10, 0x1c00
	s_add_u32 s1, s2, s1
	s_addc_u32 s6, s3, 0
	s_add_u32 s4, s1, s0
	s_addc_u32 s5, s6, 0
	s_lshl_b32 s0, s92, 9
	s_add_u32 s0, s1, s0
	s_addc_u32 s1, s6, 0
	s_lshl_b32 s6, s93, 8
	s_add_u32 s6, s0, s6
	s_addc_u32 s7, s1, 0
	s_add_i32 s0, s9, 0xffffff80
	s_ashr_i32 s0, s0, 6
	s_cmpk_gt_i32 s9, 0x80
	s_cselect_b32 s10, s0, 0
	s_ashr_i32 s87, s8, 3
	s_or_b32 s86, s87, 1
	v_mov_b32_e32 v3, v222
	s_waitcnt lgkmcnt(0)
	s_cmp_lt_i32 s86, s10
	s_cselect_b64 s[8:9], -1, 0
	s_cmp_ge_i32 s86, s10
	v_and_b32_e32 v2, 63, v3
	v_ashrrev_i32_e32 v4, 6, v3
	s_cselect_b64 s[0:1], -1, 0
	s_and_b64 vcc, exec, s[8:9]
	s_barrier
	s_cbranch_vccnz .LBB0_1995
	v_lshrrev_b32_e32 v5, 3, v2
	s_lshl_b32 s94, s86, 6
	v_lshrrev_b32_e32 v11, 4, v2
	v_lshlrev_b32_e32 v10, 4, v4
	v_xor_b32_e32 v0, v11, v2
	v_or_b32_e32 v6, s94, v5
	v_add_u32_e32 v8, v6, v10
	v_mov_b64_e32 v[6:7], s[4:5]
	v_lshlrev_b32_e32 v0, 4, v0
	v_mad_i64_i32 v[8:9], s[88:89], v8, s33, v[6:7]
	v_and_b32_e32 v0, 0x70, v0
	v_lshlrev_b32_e32 v12, 11, v4
	v_lshl_add_u64 v[8:9], v[8:9], 0, v[0:1]
	v_readfirstlane_b32 s88, v12
	v_lshl_add_u64 v[8:9], v[8:9], 0, s[18:19]
	s_mov_b32 m0, s88
	v_or_b32_e32 v13, s94, v11
	global_load_lds_dwordx4 v[8:9], off
	v_lshl_or_b32 v8, v4, 1, 1
	v_lshl_or_b32 v0, v8, 3, v5
	v_lshrrev_b32_e32 v5, 1, v0
	v_xor_b32_e32 v5, v5, v3
	v_add_u32_e32 v0, s94, v0
	v_mad_i64_i32 v[6:7], s[88:89], v0, s33, v[6:7]
	v_lshlrev_b32_e32 v0, 4, v5
	v_and_b32_e32 v0, 0x70, v0
	v_lshl_add_u64 v[6:7], v[6:7], 0, v[0:1]
	v_lshlrev_b32_e32 v0, 10, v8
	v_lshl_add_u64 v[6:7], v[6:7], 0, s[18:19]
	v_readfirstlane_b32 s88, v0
	s_mov_b32 m0, s88
	v_lshlrev_b32_e32 v0, 4, v2
	global_load_lds_dwordx4 v[6:7], off
	v_lshlrev_b32_e32 v6, 6, v11
	v_bitop3_b32 v0, v6, v0, s56 bitop3:0x78
	v_lshl_add_u64 v[6:7], s[6:7], 0, v[0:1]
	v_add_u32_e32 v0, v13, v10
	v_mad_i64_i32 v[8:9], s[88:89], v0, s33, v[6:7]
	s_movk_i32 s88, 0x2000
	s_nop 0
	v_add3_u32 v0, v12, v12, s88
	v_lshlrev_b32_e32 v5, 2, v4
	v_readfirstlane_b32 s88, v0
	v_lshl_add_u64 v[8:9], v[8:9], 0, s[20:21]
	s_mov_b32 m0, s88
	v_or_b32_e32 v0, 1, v5
	global_load_lds_dwordx4 v[8:9], off
	v_lshl_add_u32 v8, v0, 2, v13
	v_mad_i64_i32 v[8:9], s[88:89], v8, s33, v[6:7]
	v_lshl_add_u32 v0, v0, 10, v145
	v_lshl_add_u64 v[8:9], v[8:9], 0, s[20:21]
	v_readfirstlane_b32 s88, v0
	s_mov_b32 m0, s88
	v_or_b32_e32 v0, 2, v5
	global_load_lds_dwordx4 v[8:9], off
	v_lshl_add_u32 v8, v0, 2, v13
	v_mad_i64_i32 v[8:9], s[88:89], v8, s33, v[6:7]
	v_lshl_add_u32 v0, v0, 10, v145
	v_lshl_add_u64 v[8:9], v[8:9], 0, s[20:21]
	v_readfirstlane_b32 s88, v0
	v_or_b32_e32 v0, 3, v5
	v_lshl_add_u32 v5, v0, 2, v13
	s_mov_b32 m0, s88
	v_mad_i64_i32 v[6:7], s[88:89], v5, s33, v[6:7]
	v_lshl_add_u32 v0, v0, 10, v145
	global_load_lds_dwordx4 v[8:9], off
	v_readfirstlane_b32 s88, v0
	v_lshl_add_u64 v[6:7], v[6:7], 0, s[20:21]
	s_mov_b32 m0, s88
	s_nop 0
	global_load_lds_dwordx4 v[6:7], off

; DI void dil_attn_phase(const Params& p, char* smem) {
;   constexpr long LD = 3584;
;   for (;;) {
;     const int task = fetch_task(p.ctr + 2, smem);
;     if (task >= 1024) break;
.LBB0_2074:
	s_mov_b32 s98, 0
	s_load_dword s99, s[56:57], 0x170
	s_load_dwordx4 s[0:3], s[56:57], 0x108
	v_writelane_b32 v255, s24, 22
	s_mov_b32 s26, 0x41000000
	s_mov_b32 s28, 0x41200000
	v_writelane_b32 v255, s25, 23
	s_waitcnt lgkmcnt(0)
	v_writelane_b32 v255, s0, 18
	s_mov_b32 s24, 2.0
	s_mov_b32 s30, 0x41800000
	v_writelane_b32 v255, s1, 19
	v_writelane_b32 v255, s2, 20
	v_writelane_b32 v255, s3, 21
	s_load_dwordx4 s[0:3], s[56:57], 0x128
	s_mov_b32 s34, 0x41900000
	s_mov_b32 s36, 0x41c00000
	s_mov_b32 s38, 0x41d00000
	s_mov_b32 s40, 0x42680000
	s_waitcnt lgkmcnt(0)
	v_writelane_b32 v255, s0, 14
	s_mov_b32 s42, 0x42600000
	s_mov_b32 s44, 0x42480000
	v_writelane_b32 v255, s1, 15
	v_writelane_b32 v255, s2, 16
	s_mov_b32 s46, 0x42400000
	s_mov_b32 s48, 0x42280000
	s_mov_b32 s50, 0x42200000
	s_mov_b32 s52, 0x42080000
	s_mov_b32 s54, 0x42000000
	s_mov_b32 s58, -1.0
	s_mov_b32 s60, 0xc0400000
	s_mov_b32 s62, 0xc1100000
	s_mov_b32 s64, 0xc1300000
	s_mov_b32 s66, 0xc1880000
	s_mov_b32 s68, 0xc1980000
	s_mov_b32 s70, 0xc1c80000
	s_mov_b32 s72, 0xc1d80000
	s_mov_b32 s74, 0xc2040000
	s_mov_b32 s76, 0xc20c0000
	s_mov_b32 s78, 0xc2240000
	s_mov_b32 s80, 0xc22c0000
	s_mov_b32 s82, 0xc2440000
	s_mov_b32 s84, 0xc24c0000
	s_mov_b32 s86, 0xc2640000
	v_writelane_b32 v255, s3, 17
	s_mov_b32 s11, 0
	s_waitcnt vmcnt(0)
	v_mov_b32_e32 v1, 0
	v_mov_b32_e32 v148, 0x12020
	s_movk_i32 s96, 0x2000
	s_movk_i32 s56, 0x1c00
	s_movk_i32 s57, 0x7000
	s_mov_b64 s[20:21], 0x800
	s_mov_b64 s[22:23], 0xc00
	s_mov_b32 s2, 0x41400000
	s_movk_i32 s33, 0x80
	s_movk_i32 s97, 0x81
	s_mov_b32 s25, 0x40400000
	s_mov_b32 s27, 0x41100000
	s_mov_b32 s29, 0x41300000
	s_mov_b32 s31, 0x41880000
	s_mov_b32 s35, 0x41980000
	s_mov_b32 s37, 0x41c80000
	s_mov_b32 s39, 0x41d80000
	s_mov_b32 s41, 0x426c0000
	s_mov_b32 s43, 0x42640000
	s_mov_b32 s45, 0x424c0000
	s_mov_b32 s47, 0x42440000
	s_mov_b32 s49, 0x422c0000
	s_mov_b32 s51, 0x42240000
	s_mov_b32 s53, 0x420c0000
	s_mov_b32 s55, 0x42040000
	s_mov_b32 s59, -2.0
	s_mov_b32 s3, 0x43010000
	s_mov_b32 s61, 0xc1000000
	s_mov_b32 s63, 0xc1200000
	s_mov_b32 s65, 0xc1800000
	s_mov_b32 s67, 0xc1900000
	s_mov_b32 s69, 0xc1c00000
	s_mov_b32 s71, 0xc1d00000
	s_mov_b32 s73, 0xc2000000
	s_mov_b32 s75, 0xc2080000
	s_mov_b32 s77, 0xc2200000
	s_mov_b32 s79, 0xc2280000
	s_mov_b32 s81, 0xc2400000
	s_mov_b32 s83, 0xc2480000
	s_mov_b32 s85, 0xc2600000
	s_mov_b32 s87, 0xc2680000
	s_mov_b32 s12, 0x1c000
	s_mov_b64 s[88:89], 0xa00
	v_mov_b32_e32 v149, 0x2000
	v_mov_b32_e32 v150, 0x6000
	v_mov_b32_e32 v151, 0x8000
	v_mov_b32_e32 v152, 0x42800000
	v_mov_b32_e32 v153, 0xff800000
	s_branch .LBB0_2077

; DI int ltid() { int x = threadIdx.x; asm volatile("" : "+v"(x)); return x; }
; DI int fetch_task(unsigned* ctr, char* smem) {
;   unsigned* slot = (unsigned*)(smem + SM_TASK);
;   __syncthreads();
;   if (ltid() == 0) *slot = atomicAdd(ctr, 1u);
;   __syncthreads();
;   return (int)*slot;
; }
.LBB0_2077:
	v_mov_b32_e32 v0, v222
	s_barrier
	s_nop 0
	v_cmp_eq_u32_e32 vcc, 0, v0
	s_and_saveexec_b64 s[0:1], vcc
	s_cbranch_execz .LBB0_2081
	s_mov_b64 s[6:7], exec
	v_mbcnt_lo_u32_b32 v0, s6, 0
	v_mbcnt_hi_u32_b32 v0, s7, v0
	v_cmp_eq_u32_e32 vcc, 0, v0
	s_and_saveexec_b64 s[4:5], vcc
	s_cbranch_execz .LBB0_2080
	s_bcnt1_i32_b64 s6, s[6:7]
	v_readlane_b32 s16, v255, 18
	v_mov_b32_e32 v2, s6
	v_readlane_b32 s17, v255, 19
	v_readlane_b32 s18, v255, 20
	v_readlane_b32 s19, v255, 21
	s_nop 2
	s_cmp_eq_u32 s98, 0
	s_cbranch_scc1 .Lft_skip_dil
	global_atomic_add v2, v1, v2, s[16:17] offset:8 sc0

; DI int ltid() { int x = threadIdx.x; asm volatile("" : "+v"(x)); return x; }
; DI void dil_attn_phase(const Params& p, char* smem) {
;     ...
;     const int task = fetch_task(p.ctr + 2, smem);
;     if (task >= 1024) break;
;     const int tid = ltid(), lane = tid & 63, wid = tid >> 6, r = lane & 31, h = lane >> 5;
;     const int half = task & 1, hg = (task >> 1) & 3, b = (task >> 3) & 1, grp = task >> 4;
;     const int r16 = grp & 15, U0 = (grp >> 4) * 128;
;     const int u16q = U0 + wid * 32 + r;
;     const int pos = r16 + 16 * u16q;
;     const long tok = (long)b * SEQ + pos;
;     f32x16 ot[4];
;     float m = 0.f, l = 0.f;
; #pragma unroll
;     for (int dc = 0; dc < 4; ++dc)
; #pragma unroll
;       for (int i = 0; i < 16; ++i) ot[dc][i] = 0.f;
; #pragma unroll
;     for (int g = 1; g < 3; ++g) {
;       const int d = (g == 1) ? 4 : 16;
;       const int res = pos % d;
;       const int uq = pos / d;
;       const int wpos0 = r16 + 16 * (U0 + wid * 32), wpos1 = wpos0 + 16 * 31;
;       const int wq_min = wpos0 / d, wq_max = wpos1 / d;
;       const int gpos0 = r16 + 16 * U0, gpos1 = gpos0 + 16 * 127;
;       const int gq_min = gpos0 / d, gq_max = gpos1 / d;
;       const int tlo = (gq_min - 128) > 0 ? ((gq_min - 128) >> 6) : 0;
;       const int thi = (gq_max >> 6) + 1;
;       const float slope = exp2f(-8.f * (float)(4 * g + hg + 1) / 12.f);
;       const float slope2 = slope * (float)d * LOG2E;
;       bf16x8 qf[4];
;       load_q(qf, p.qkvz + tok * LD + g * 256 + hg * 64, h);
;       const u16* kb_ = p.qkvz + ((long)b * SEQ + res) * LD + 768 + g * 256 + hg * 64;
;       const u16* vb_ = p.qkvz + ((long)b * SEQ + res) * LD + 1536 + hg * 256 + half * 128;
;       flash_pass<128, false, false>(smem, kb_, LD * d, vb_, LD * d, tlo, thi, nullptr, qf, uq, 1, 129, slope2, wq_min, wq_max, nullptr, 0.f, ot, m, l);
.LBB0_2081:
	s_or_b64 exec, exec, s[0:1]
	s_waitcnt lgkmcnt(0)
	s_barrier
	ds_read_b32 v0, v148
	s_mov_b32 s98, 1
	s_movk_i32 s0, 0x3ff
	s_waitcnt lgkmcnt(0)
	v_cmp_lt_i32_e32 vcc, s0, v0
	v_readfirstlane_b32 s4, v0
	s_mov_b64 s[0:1], -1
	s_cbranch_vccnz .LBB0_2076
	v_mov_b32_e32 v0, v222
	s_ashr_i32 s0, s4, 1
	v_ashrrev_i32_e32 v2, 1, v0
	s_and_b32 s0, s0, 0xffffff80
	v_and_b32_e32 v2, 0xffffffe0, v2
	s_lshl_b32 s1, s4, 10
	s_bfe_u32 s6, s4, 0x40004
	v_add_u32_e32 v9, s0, v2
	s_and_b32 s10, s1, 0x2000
	s_lshl_b32 s1, s0, 4
	s_bfe_i32 s0, s0, 0x1001b
	s_or_b32 s91, s1, s6
	s_lshr_b32 s0, s0, 30
	s_add_i32 s1, s91, s0
	v_and_or_b32 v6, v0, 31, v9
	s_ashr_i32 s1, s1, 2
	v_lshl_or_b32 v132, v6, 4, s6
	s_or_b32 s16, s91, 0x7f0
	s_addk_i32 s1, 0xff80
	v_readlane_b32 s92, v255, 14
	v_ashrrev_i32_e32 v133, 31, v132
	s_and_b32 s13, s4, 1
	s_bfe_u32 s14, s4, 0x20001
	s_add_i32 s7, s16, s0
	s_ashr_i32 s0, s1, 6
	v_readlane_b32 s94, v255, 16
	v_readlane_b32 s95, v255, 17
	v_lshl_add_u64 v[128:129], v[132:133], 0, s[10:11]
	s_cmpk_gt_i32 s91, 0x203
	v_mov_b64_e32 v[2:3], s[94:95]
	s_cselect_b32 s15, s0, 0
	v_mad_u64_u32 v[130:131], s[0:1], v128, s56, v[2:3]
	v_bfe_u32 v154, v0, 5, 1
	v_mad_i32_i24 v131, v129, s56, v131
	s_lshl_b32 s0, s14, 7
	s_mov_b32 s1, s11
	v_lshl_add_u64 v[4:5], v[130:131], 0, s[0:1]
	v_lshlrev_b32_e32 v0, 4, v154
	v_lshl_add_u64 v[134:135], v[4:5], 0, v[0:1]
	global_load_dwordx4 v[112:115], v[134:135], off offset:512
	global_load_dwordx4 v[116:119], v[134:135], off offset:544
	global_load_dwordx4 v[120:123], v[134:135], off offset:576
	global_load_dwordx4 v[124:127], v[134:135], off offset:608
	v_bfe_i32 v0, v6, 27, 1
	v_lshrrev_b32_e32 v0, 30, v0
	v_add_u32_e32 v10, v132, v0
	v_and_b32_e32 v0, -4, v10
	v_sub_u32_e32 v4, v132, v0
	v_ashrrev_i32_e32 v5, 31, v4
	v_lshl_add_u64 v[4:5], v[4:5], 0, s[10:11]
	v_mad_u64_u32 v[6:7], s[4:5], v4, s56, v[2:3]
	v_mad_i32_i24 v7, v5, s56, v7
	v_lshl_add_u64 v[2:3], v[6:7], 0, s[0:1]
	s_lshl_b32 s0, s14, 9
	s_ashr_i32 s8, s7, 8
	v_lshl_add_u64 v[4:5], v[6:7], 0, s[0:1]
	s_lshl_b32 s0, s13, 8
	v_mov_b32_e32 v7, v222
	s_waitcnt lgkmcnt(0)
	s_cmp_lt_i32 s8, s15
	s_cselect_b64 s[4:5], -1, 0
	s_cmp_ge_i32 s8, s15
	v_lshl_add_u64 v[4:5], v[4:5], 0, s[0:1]
	v_and_b32_e32 v6, 63, v7
	v_ashrrev_i32_e32 v8, 6, v7
	s_cselect_b64 s[0:1], -1, 0
	s_and_b64 vcc, exec, s[4:5]
	v_readlane_b32 s93, v255, 15
	s_barrier
	s_cbranch_vccnz .LBB0_2084
	s_ashr_i32 s7, s7, 2
	v_lshrrev_b32_e32 v11, 3, v6
	s_andn2_b32 s7, s7, 63
	v_lshrrev_b32_e32 v15, 4, v6
	v_lshlrev_b32_e32 v14, 4, v8
	v_xor_b32_e32 v0, v15, v6
	v_or_b32_e32 v12, s7, v11
	v_add_u32_e32 v12, v12, v14
	v_lshlrev_b32_e32 v0, 4, v0
	v_mad_i64_i32 v[12:13], s[18:19], v12, s57, v[2:3]
	v_and_b32_e32 v0, 0x70, v0
	v_lshl_or_b32 v17, v8, 1, 1
	v_lshl_add_u64 v[12:13], v[12:13], 0, v[0:1]
	v_lshlrev_b32_e32 v16, 11, v8
	v_lshl_or_b32 v0, v17, 3, v11
	v_readfirstlane_b32 s9, v16
	v_lshrrev_b32_e32 v11, 1, v0
	v_lshl_add_u64 v[12:13], v[12:13], 0, s[20:21]
	s_mov_b32 m0, s9
	v_xor_b32_e32 v11, v11, v7
	v_add_u32_e32 v0, s7, v0
	global_load_lds_dwordx4 v[12:13], off
	v_mad_i64_i32 v[12:13], s[18:19], v0, s57, v[2:3]
	v_lshlrev_b32_e32 v0, 4, v11
	v_and_b32_e32 v0, 0x70, v0
	v_lshl_add_u64 v[12:13], v[12:13], 0, v[0:1]
	v_lshlrev_b32_e32 v0, 10, v17
	v_lshl_add_u64 v[12:13], v[12:13], 0, s[20:21]
	v_readfirstlane_b32 s9, v0
	s_mov_b32 m0, s9
	v_or_b32_e32 v17, s7, v15
	global_load_lds_dwordx4 v[12:13], off
	v_lshlrev_b32_e32 v0, 4, v6
	v_lshlrev_b32_e32 v12, 6, v15
	s_movk_i32 s7, 0xf0
	v_bitop3_b32 v0, v12, v0, s7 bitop3:0x78
	v_lshl_add_u64 v[12:13], v[4:5], 0, v[0:1]
	v_add_u32_e32 v0, v17, v14
	v_mad_i64_i32 v[14:15], s[18:19], v0, s57, v[12:13]
	v_add3_u32 v0, v16, v16, s96
	v_lshlrev_b32_e32 v11, 2, v8
	v_readfirstlane_b32 s7, v0
	v_lshl_add_u64 v[14:15], v[14:15], 0, s[22:23]
	s_mov_b32 m0, s7
	v_or_b32_e32 v0, 1, v11
	global_load_lds_dwordx4 v[14:15], off
	v_lshl_add_u32 v14, v0, 2, v17
	v_lshl_add_u32 v0, v0, 10, v149
	v_mad_i64_i32 v[14:15], s[18:19], v14, s57, v[12:13]
	v_readfirstlane_b32 s7, v0
	v_lshl_add_u64 v[14:15], v[14:15], 0, s[22:23]
	s_mov_b32 m0, s7
	v_or_b32_e32 v0, 2, v11
	global_load_lds_dwordx4 v[14:15], off
	v_lshl_add_u32 v14, v0, 2, v17
	v_lshl_add_u32 v0, v0, 10, v149
	v_mad_i64_i32 v[14:15], s[18:19], v14, s57, v[12:13]
	v_readfirstlane_b32 s7, v0
	v_or_b32_e32 v0, 3, v11
	v_lshl_add_u32 v11, v0, 2, v17
	v_lshl_add_u32 v0, v0, 10, v149
	v_lshl_add_u64 v[14:15], v[14:15], 0, s[22:23]
	s_mov_b32 m0, s7
	v_mad_i64_i32 v[12:13], s[18:19], v11, s57, v[12:13]
	v_readfirstlane_b32 s7, v0
	global_load_lds_dwordx4 v[14:15], off
	v_lshl_add_u64 v[12:13], v[12:13], 0, s[22:23]
	s_mov_b32 m0, s7
	s_nop 0
	global_load_lds_dwordx4 v[12:13], off

; DI void stick_attn_phase(const Params& p, char* smem) {
;   constexpr long LD = 4096;
;   unsigned* flags = (unsigned*)(smem + SM_FLAG);
;   for (;;) {
;     const int task = fetch_task(p.ctr + 3, smem);
.LBB0_2597:
	s_mov_b32 s98, 0
	s_load_dword s99, s[56:57], 0x170
	s_load_dwordx2 s[2:3], s[56:57], 0x108
	s_load_dwordx4 s[12:15], s[56:57], 0x128
	s_mov_b32 s19, 0
	s_waitcnt vmcnt(0)
	v_mov_b32_e32 v1, 0
	v_mov_b32_e32 v110, 0x12020
	s_movk_i32 s28, 0x7ff
	s_mov_b64 s[20:21], 0x800
	s_mov_b64 s[22:23], 0x1000
	s_mov_b32 s29, 0xbfb8aa3b
	s_mov_b32 s30, 0xc2d20000
	s_mov_b64 s[24:25], 0x1800
	v_mov_b32_e32 v111, 0x12000
	v_mov_b32_e32 v112, 0xff800000
	s_branch .LBB0_2600

; DI int ltid() { int x = threadIdx.x; asm volatile("" : "+v"(x)); return x; }
; DI int fetch_task(unsigned* ctr, char* smem) {
;   unsigned* slot = (unsigned*)(smem + SM_TASK);
;   __syncthreads();
;   if (ltid() == 0) *slot = atomicAdd(ctr, 1u);
;   __syncthreads();
;   return (int)*slot;
; }
.LBB0_2600:
	v_mov_b32_e32 v0, v222
	s_waitcnt lgkmcnt(0)
	s_barrier
	s_nop 0
	v_cmp_eq_u32_e32 vcc, 0, v0
	s_and_saveexec_b64 s[0:1], vcc
	s_cbranch_execz .LBB0_2604
	s_mov_b64 s[6:7], exec
	v_mbcnt_lo_u32_b32 v0, s6, 0
	v_mbcnt_hi_u32_b32 v0, s7, v0
	v_cmp_eq_u32_e32 vcc, 0, v0
	s_and_saveexec_b64 s[4:5], vcc
	s_cbranch_execz .LBB0_2603
	s_bcnt1_i32_b64 s6, s[6:7]
	v_mov_b32_e32 v2, s6
	s_cmp_eq_u32 s98, 0
	s_cbranch_scc1 .Lft_skip_stick
	global_atomic_add v2, v1, v2, s[2:3] offset:12 sc0

; DI int ltid() { int x = threadIdx.x; asm volatile("" : "+v"(x)); return x; }
; #define RAW_BARRIER() do { asm volatile("s_waitcnt lgkmcnt(0)" ::: "memory"); __builtin_amdgcn_s_barrier(); } while (0)
; DI int fetch_task(unsigned* ctr, char* smem) {
;   unsigned* slot = (unsigned*)(smem + SM_TASK);
;   __syncthreads();
;   if (ltid() == 0) *slot = atomicAdd(ctr, 1u);
;   __syncthreads();
;   return (int)*slot;
; }
; DI void stick_attn_phase(const Params& p, char* smem) {
;     ...
;     const int task = fetch_task(p.ctr + 3, smem);
;     if (task >= 2048) break;
;     const int tid = ltid(), lane = tid & 63, wid = tid >> 6, r = lane & 31, h = lane >> 5;
;     const int qt = 63 - (task >> 5), bh = task & 31, b = bh >> 4, hd = bh & 15;
;     const int q0 = qt * 128 + wid * 32, tq = q0 + r;
;     const long tok = (long)b * SEQ + tq;
;     bf16x8 qf[4];
;     load_q(qf, p.qkvz + tok * LD + hd * 64, h);
;     const u16* kb_ = p.qkvz + (long)b * SEQ * LD + 1024 + hd * 64;
;     const u16* vb_ = p.qkvz + (long)b * SEQ * LD + 2048 + hd * 64;
;     f32x16 ot[2];
; #pragma unroll
;     for (int dc = 0; dc < 2; ++dc)
; #pragma unroll
;       for (int i = 0; i < 16; ++i) ot[dc][i] = 0.f;
;     float carry = 0.f;
;     unsigned done = 0u;
;     int foff[4];
;     make_foff(foff, r, h);
;     RAW_BARRIER();
;     int t = ((qt * 128 + 127) >> 6);
;     kv_issue<64, true>(smem, 0, kb_, LD, vb_, LD, t, lane, wid);
;     if (t >= 1) kv_issue<64, true>(smem, 1, kb_, LD, vb_, LD, t - 1, lane, wid);
;     int c = 0;
.Lft_st_stick:
	ds_write_b32 v110, v0
.LBB0_2604:
	s_or_b64 exec, exec, s[0:1]
	s_waitcnt lgkmcnt(0)
	s_barrier
	ds_read_b32 v0, v110
	s_mov_b32 s98, 1
	s_mov_b64 s[0:1], -1
	s_waitcnt lgkmcnt(0)
	v_cmp_lt_i32_e32 vcc, s28, v0
	v_readfirstlane_b32 s4, v0
	s_cbranch_vccnz .LBB0_2599
	v_mov_b32_e32 v6, v222
	s_lshl_b32 s0, s4, 2
	v_ashrrev_i32_e32 v7, 6, v6
	s_and_b32 s8, s0, 0xffffff80
	v_lshlrev_b32_e32 v0, 5, v7
	v_subrev_u32_e32 v10, s8, v0
	v_and_b32_e32 v8, 31, v6
	v_add_u32_e32 v113, 0x1f80, v10
	v_or_b32_e32 v98, v113, v8
	s_lshl_b32 s0, s4, 9
	s_and_b32 s18, s0, 0x2000
	v_ashrrev_i32_e32 v99, 31, v98
	v_lshl_add_u64 v[96:97], v[98:99], 0, s[18:19]
	s_lshl_b32 s0, s4, 6
	v_lshlrev_b64 v[2:3], 13, v[96:97]
	s_and_b32 s31, s0, 0x3c0
	v_lshl_add_u64 v[100:101], s[14:15], 0, v[2:3]
	s_lshl_b32 s0, s31, 1
	s_mov_b32 s1, s19
	v_lshl_add_u64 v[2:3], v[100:101], 0, s[0:1]
	s_lshl_b32 s1, s18, 13
	s_add_u32 s1, s14, s1
	v_bfe_u32 v9, v6, 5, 1
	s_addc_u32 s4, s15, 0
	v_lshlrev_b32_e32 v0, 4, v9
	s_add_u32 s0, s1, s0
	v_bfe_u32 v11, v6, 3, 3
	v_lshlrev_b32_e32 v12, 4, v7
	v_lshl_add_u64 v[2:3], v[2:3], 0, v[0:1]
	s_addc_u32 s1, s4, 0
	s_sub_i32 s4, 0x1fc0, s8
	v_or_b32_e32 v99, v12, v11
	global_load_dwordx4 v[80:83], v[2:3], off
	global_load_dwordx4 v[84:87], v[2:3], off offset:32
	global_load_dwordx4 v[88:91], v[2:3], off offset:64
	global_load_dwordx4 v[92:95], v[2:3], off offset:96
	v_bfe_u32 v0, v6, 4, 2
	v_add_u32_e32 v2, s4, v99
	v_xor_b32_e32 v0, v0, v6
	v_ashrrev_i32_e32 v3, 31, v2
	v_lshlrev_b64 v[2:3], 13, v[2:3]
	v_lshlrev_b32_e32 v0, 4, v0
	v_lshl_add_u64 v[2:3], s[0:1], 0, v[2:3]
	v_and_b32_e32 v0, 0x70, v0
	v_lshlrev_b32_e32 v13, 11, v7
	v_lshl_or_b32 v14, v7, 1, 1
	v_lshl_add_u64 v[2:3], v[2:3], 0, v[0:1]
	v_readfirstlane_b32 s5, v13
	v_lshlrev_b32_e32 v15, 3, v14
	v_lshl_add_u64 v[2:3], v[2:3], 0, s[20:21]
	s_mov_b32 m0, s5
	v_or_b32_e32 v16, v15, v11
	s_waitcnt lgkmcnt(0)
	s_barrier
	global_load_lds_dwordx4 v[2:3], off
	v_lshrrev_b32_e32 v2, 1, v16
	v_xor_b32_e32 v4, v2, v6
	v_add_u32_e32 v2, s4, v16
	v_ashrrev_i32_e32 v3, 31, v2
	v_lshlrev_b64 v[2:3], 13, v[2:3]
	v_lshlrev_b32_e32 v4, 4, v4
	v_lshl_add_u64 v[2:3], s[0:1], 0, v[2:3]
	v_and_b32_e32 v4, 0x70, v4
	v_mov_b32_e32 v5, v1
	v_lshlrev_b32_e32 v14, 10, v14
	v_lshl_add_u64 v[2:3], v[2:3], 0, v[4:5]
	v_readfirstlane_b32 s5, v14
	v_lshl_add_u64 v[2:3], v[2:3], 0, s[20:21]
	s_mov_b32 m0, s5
	v_or_b32_e32 v17, s4, v11
	global_load_lds_dwordx4 v[2:3], off
	v_and_b32_e32 v2, 7, v6
	v_bfe_u32 v3, v6, 2, 4
	v_bitop3_b32 v2, v3, v2, 4 bitop3:0x6c
	v_lshlrev_b32_e32 v2, 4, v2
	v_mov_b32_e32 v3, v1
	v_lshl_add_u64 v[2:3], s[0:1], 0, v[2:3]
	v_lshl_add_u64 v[102:103], v[2:3], 0, s[22:23]
	v_add_u32_e32 v2, v17, v12
	v_ashrrev_i32_e32 v3, 31, v2
	v_add_u32_e32 v18, 0x2000, v13
	v_lshlrev_b64 v[2:3], 13, v[2:3]
	v_readfirstlane_b32 s5, v18
	v_lshl_add_u64 v[2:3], v[102:103], 0, v[2:3]
	s_mov_b32 m0, s5
	v_lshl_add_u64 v[106:107], s[0:1], 0, v[4:5]
	global_load_lds_dwordx4 v[2:3], off
	v_add_u32_e32 v2, v15, v17
	v_ashrrev_i32_e32 v3, 31, v2
	v_add_u32_e32 v17, 0x2000, v14
	v_lshlrev_b64 v[2:3], 13, v[2:3]
	v_readfirstlane_b32 s5, v17
	v_lshl_add_u64 v[2:3], v[102:103], 0, v[2:3]
	s_mov_b32 m0, s5
	s_sub_i32 s5, 0x1f80, s8
	global_load_lds_dwordx4 v[2:3], off
	v_add_u32_e32 v2, s5, v99
	v_ashrrev_i32_e32 v3, 31, v2
	v_lshlrev_b64 v[2:3], 13, v[2:3]
	v_lshl_add_u64 v[2:3], s[0:1], 0, v[2:3]
	v_add_u32_e32 v17, 0x4000, v13
	v_lshl_add_u64 v[2:3], v[2:3], 0, v[0:1]
	v_readfirstlane_b32 s6, v17
	v_lshl_add_u64 v[2:3], v[2:3], 0, s[20:21]
	s_mov_b32 m0, s6
	s_lshr_b32 s33, s4, 6
	global_load_lds_dwordx4 v[2:3], off
	v_add_u32_e32 v2, s5, v16
	v_ashrrev_i32_e32 v3, 31, v2
	v_lshlrev_b64 v[2:3], 13, v[2:3]
	v_lshl_add_u64 v[2:3], s[0:1], 0, v[2:3]
	v_add_u32_e32 v16, 0x4000, v14
	v_lshl_add_u64 v[2:3], v[2:3], 0, v[4:5]
	v_readfirstlane_b32 s6, v16
	v_lshl_add_u64 v[2:3], v[2:3], 0, s[20:21]
	s_mov_b32 m0, s6
	v_or_b32_e32 v16, s5, v11
	global_load_lds_dwordx4 v[2:3], off
	v_add_u32_e32 v2, v16, v12
	v_ashrrev_i32_e32 v3, 31, v2
	v_add_u32_e32 v12, 0x6000, v13
	v_lshlrev_b64 v[2:3], 13, v[2:3]
	v_readfirstlane_b32 s5, v12
	v_lshl_add_u64 v[2:3], v[102:103], 0, v[2:3]
	s_mov_b32 m0, s5
	v_add_u32_e32 v12, 0x6000, v14
	global_load_lds_dwordx4 v[2:3], off
	v_add_u32_e32 v2, v15, v16
	v_ashrrev_i32_e32 v3, 31, v2
	v_lshlrev_b64 v[2:3], 13, v[2:3]
	v_readfirstlane_b32 s5, v12
	v_lshl_add_u64 v[2:3], v[102:103], 0, v[2:3]
	s_mov_b32 m0, s5
	v_bfe_u32 v12, v6, 1, 3
	global_load_lds_dwordx4 v[2:3], off
	v_and_b32_e32 v2, 63, v6
	v_lshlrev_b32_e32 v4, 1, v6
	v_lshlrev_b32_e32 v3, 7, v8
	v_lshrrev_b32_e32 v8, 1, v6
	v_bitop3_b32 v14, v9, v12, 2 bitop3:0x36
	v_bitop3_b32 v15, v9, v12, 4 bitop3:0x36
	v_lshl_add_u64 v[104:105], s[0:1], 0, v[0:1]
	v_cmp_eq_u32_e64 s[4:5], 0, v2
	v_cmp_gt_u32_e64 s[6:7], 32, v2
	v_bfe_u32 v0, v2, 2, 2
	v_and_b32_e32 v4, 32, v4
	v_lshlrev_b32_e32 v2, 3, v2
	v_bitop3_b32 v8, v9, v8, 7 bitop3:0x78
	v_bitop3_b32 v12, v9, v12, 6 bitop3:0x36
	v_and_or_b32 v0, v11, 4, v0
	v_and_or_b32 v4, v2, 24, v4
	v_lshl_or_b32 v125, v15, 4, v3
	v_lshl_or_b32 v127, v14, 4, v3
	v_mov_b32_e32 v14, v1
	v_mov_b32_e32 v15, v1
	v_lshl_add_u32 v114, v7, 2, v111
	v_add_u32_e32 v116, 0x1f9f, v10
	v_lshlrev_b32_e32 v115, 2, v9
	v_lshl_or_b32 v117, v0, 7, v4
	v_and_b32_e32 v118, 64, v2
	v_bitop3_b32 v119, v2, 64, v2 bitop3:0xc
	v_add_u32_e32 v120, 0xa400, v13
	v_add_u32_e32 v121, 0x8400, v13
	v_add_u32_e32 v122, 0xa000, v13
	v_add_u32_e32 v123, 0x8000, v13
	v_lshl_or_b32 v124, v12, 4, v3
	v_lshl_or_b32 v126, v8, 4, v3
	v_mov_b32_e32 v0, v1
	v_mov_b32_e32 v2, v1
	v_mov_b32_e32 v3, v1
	v_mov_b32_e32 v4, v1
	v_mov_b32_e32 v6, v1
	v_mov_b32_e32 v7, v1
	v_mov_b32_e32 v8, v1
	v_mov_b32_e32 v9, v1
	v_mov_b32_e32 v10, v1
	v_mov_b32_e32 v11, v1
	v_mov_b32_e32 v12, v1
	v_mov_b32_e32 v13, v1
	v_mov_b64_e32 v[30:31], v[14:15]
	v_mov_b64_e32 v[46:47], v[14:15]
	s_mov_b32 s18, 2
	s_mov_b32 s34, 0
	s_sub_i32 s35, 0x1fff, s8
	v_mov_b32_e32 v109, 0
	v_mov_b32_e32 v48, 0
	s_mov_b32 s36, 0
	v_mov_b64_e32 v[28:29], v[12:13]
	v_mov_b64_e32 v[26:27], v[10:11]
	v_mov_b64_e32 v[24:25], v[8:9]
	v_mov_b64_e32 v[22:23], v[6:7]
	v_mov_b64_e32 v[20:21], v[4:5]
	v_mov_b64_e32 v[18:19], v[2:3]
	v_mov_b64_e32 v[16:17], v[0:1]
	s_mov_b32 s37, 0
	v_mov_b64_e32 v[44:45], v[12:13]
	v_mov_b64_e32 v[42:43], v[10:11]
	v_mov_b64_e32 v[40:41], v[8:9]
	v_mov_b64_e32 v[38:39], v[6:7]
	v_mov_b64_e32 v[36:37], v[4:5]
	v_mov_b64_e32 v[34:35], v[2:3]
	v_mov_b64_e32 v[32:33], v[0:1]
	s_waitcnt vmcnt(0)
	s_branch .LBB0_2607
